# prep modulation partial sums: weight rows preloaded per job, accumulation as plain f32 FMAs fully unrolled; barrier census loads batched
# speedup vs baseline: 1.0064x; 1.0001x over previous
.Lcvt_join:
	s_mov_b64 exec, s[18:19]
	s_mov_b64 s[4:5], exec
	s_waitcnt vmcnt(0)
	ds_write_b32 v4, v21
	ds_write_b32 v5, v22
	ds_write_b32 v7, v23
	ds_write_b32 v9, v24
	ds_write_b32 v11, v25
	ds_write_b32 v13, v26
	ds_write_b32 v15, v27
	s_branch .LBB0_438
	s_nop 0
	s_nop 0
	s_nop 0
	s_nop 0
	s_nop 0
	s_nop 0
	s_nop 0
	s_nop 0
	s_nop 0
	s_nop 0
	s_nop 0
	s_nop 0
	s_nop 0
	s_nop 0
	s_nop 0
	s_nop 0
	s_nop 0
	s_nop 0
	s_nop 0
	s_nop 0
	s_nop 0
	s_nop 0
	s_nop 0
	s_nop 0
	s_nop 0
	s_nop 0
	s_nop 0

.LBB0_551:
	s_and_b32 s18, s23, 3
	s_barrier
	s_and_b32 s2, s22, 3
	s_lshl_b32 s14, s2, 8
	s_ashr_i32 s2, s23, 2
	s_mul_hi_i32 s3, s2, 0x2aaaaaab
	s_lshr_b32 s10, s3, 31
	s_lshr_b32 s3, s3, 3
	s_add_i32 s3, s3, s10
	s_mul_i32 s3, s3, 48
	s_sub_i32 s12, s2, s3
	s_mul_hi_i32 s2, s23, 0x2aaaaaab
	s_lshr_b32 s3, s2, 31
	s_ashr_i32 s2, s2, 5
	s_add_i32 s2, s2, s3
	s_ashr_i32 s3, s2, 31
	s_lshl_b64 s[10:11], s[2:3], 10
	s_lshl_b32 s12, s12, 7
	s_ashr_i32 s13, s12, 31
	s_or_b32 s10, s10, s14
	v_lshl_add_u64 v[10:11], s[10:11], 0, v[0:1]
	s_lshl_b64 s[10:11], s[12:13], 2
	v_mov_b64_e32 v[12:13], s[10:11]
	v_mad_u64_u32 v[12:13], s[10:11], v10, s67, v[12:13]
	v_mad_i32_i24 v13, v11, s67, v13
	v_lshl_add_u64 v[144:145], v[8:9], 0, v[12:13]
	s_mov_b32 s98, 0xffff4000
	s_mov_b32 s99, -1
	v_lshl_add_u64 v[144:145], v[144:145], 0, s[98:99]
	s_mov_b64 s[98:99], 0x6000
	global_load_dword v80, v[144:145], off
	v_lshl_add_u64 v[144:145], v[144:145], 0, s[98:99]
	global_load_dword v81, v[144:145], off
	v_lshl_add_u64 v[144:145], v[144:145], 0, s[98:99]
	global_load_dword v82, v[144:145], off
	v_lshl_add_u64 v[144:145], v[144:145], 0, s[98:99]
	global_load_dword v83, v[144:145], off
	v_lshl_add_u64 v[144:145], v[144:145], 0, s[98:99]
	global_load_dword v84, v[144:145], off
	v_lshl_add_u64 v[144:145], v[144:145], 0, s[98:99]
	global_load_dword v85, v[144:145], off
	v_lshl_add_u64 v[144:145], v[144:145], 0, s[98:99]
	global_load_dword v86, v[144:145], off
	v_lshl_add_u64 v[144:145], v[144:145], 0, s[98:99]
	global_load_dword v87, v[144:145], off
	v_lshl_add_u64 v[144:145], v[144:145], 0, s[98:99]
	global_load_dword v88, v[144:145], off
	v_lshl_add_u64 v[144:145], v[144:145], 0, s[98:99]
	global_load_dword v89, v[144:145], off
	v_lshl_add_u64 v[144:145], v[144:145], 0, s[98:99]
	global_load_dword v90, v[144:145], off
	v_lshl_add_u64 v[144:145], v[144:145], 0, s[98:99]
	global_load_dword v91, v[144:145], off
	v_lshl_add_u64 v[144:145], v[144:145], 0, s[98:99]
	global_load_dword v92, v[144:145], off
	v_lshl_add_u64 v[144:145], v[144:145], 0, s[98:99]
	global_load_dword v93, v[144:145], off
	v_lshl_add_u64 v[144:145], v[144:145], 0, s[98:99]
	global_load_dword v94, v[144:145], off
	v_lshl_add_u64 v[144:145], v[144:145], 0, s[98:99]
	global_load_dword v95, v[144:145], off
	v_lshl_add_u64 v[144:145], v[144:145], 0, s[98:99]
	global_load_dword v96, v[144:145], off
	v_lshl_add_u64 v[144:145], v[144:145], 0, s[98:99]
	global_load_dword v97, v[144:145], off
	v_lshl_add_u64 v[144:145], v[144:145], 0, s[98:99]
	global_load_dword v98, v[144:145], off
	v_lshl_add_u64 v[144:145], v[144:145], 0, s[98:99]
	global_load_dword v99, v[144:145], off
	v_lshl_add_u64 v[144:145], v[144:145], 0, s[98:99]
	global_load_dword v100, v[144:145], off
	v_lshl_add_u64 v[144:145], v[144:145], 0, s[98:99]
	global_load_dword v101, v[144:145], off
	v_lshl_add_u64 v[144:145], v[144:145], 0, s[98:99]
	global_load_dword v102, v[144:145], off
	v_lshl_add_u64 v[144:145], v[144:145], 0, s[98:99]
	global_load_dword v103, v[144:145], off
	v_lshl_add_u64 v[144:145], v[144:145], 0, s[98:99]
	global_load_dword v104, v[144:145], off
	v_lshl_add_u64 v[144:145], v[144:145], 0, s[98:99]
	global_load_dword v105, v[144:145], off
	v_lshl_add_u64 v[144:145], v[144:145], 0, s[98:99]
	global_load_dword v106, v[144:145], off
	v_lshl_add_u64 v[144:145], v[144:145], 0, s[98:99]
	global_load_dword v107, v[144:145], off
	v_lshl_add_u64 v[144:145], v[144:145], 0, s[98:99]
	global_load_dword v108, v[144:145], off
	v_lshl_add_u64 v[144:145], v[144:145], 0, s[98:99]
	global_load_dword v109, v[144:145], off
	v_lshl_add_u64 v[144:145], v[144:145], 0, s[98:99]
	global_load_dword v110, v[144:145], off
	v_lshl_add_u64 v[144:145], v[144:145], 0, s[98:99]
	global_load_dword v111, v[144:145], off
	v_lshl_add_u64 v[144:145], v[144:145], 0, s[98:99]
	global_load_dword v112, v[144:145], off
	v_lshl_add_u64 v[144:145], v[144:145], 0, s[98:99]
	global_load_dword v113, v[144:145], off
	v_lshl_add_u64 v[144:145], v[144:145], 0, s[98:99]
	global_load_dword v114, v[144:145], off
	v_lshl_add_u64 v[144:145], v[144:145], 0, s[98:99]
	global_load_dword v115, v[144:145], off
	v_lshl_add_u64 v[144:145], v[144:145], 0, s[98:99]
	global_load_dword v116, v[144:145], off
	v_lshl_add_u64 v[144:145], v[144:145], 0, s[98:99]
	global_load_dword v117, v[144:145], off
	v_lshl_add_u64 v[144:145], v[144:145], 0, s[98:99]
	global_load_dword v118, v[144:145], off
	v_lshl_add_u64 v[144:145], v[144:145], 0, s[98:99]
	global_load_dword v119, v[144:145], off
	v_lshl_add_u64 v[144:145], v[144:145], 0, s[98:99]
	global_load_dword v120, v[144:145], off
	v_lshl_add_u64 v[144:145], v[144:145], 0, s[98:99]
	global_load_dword v121, v[144:145], off
	v_lshl_add_u64 v[144:145], v[144:145], 0, s[98:99]
	global_load_dword v122, v[144:145], off
	v_lshl_add_u64 v[144:145], v[144:145], 0, s[98:99]
	global_load_dword v123, v[144:145], off
	v_lshl_add_u64 v[144:145], v[144:145], 0, s[98:99]
	global_load_dword v124, v[144:145], off
	v_lshl_add_u64 v[144:145], v[144:145], 0, s[98:99]
	global_load_dword v125, v[144:145], off
	v_lshl_add_u64 v[144:145], v[144:145], 0, s[98:99]
	global_load_dword v126, v[144:145], off
	v_lshl_add_u64 v[144:145], v[144:145], 0, s[98:99]
	global_load_dword v127, v[144:145], off
	v_lshl_add_u64 v[144:145], v[144:145], 0, s[98:99]
	global_load_dword v128, v[144:145], off
	v_lshl_add_u64 v[144:145], v[144:145], 0, s[98:99]
	global_load_dword v129, v[144:145], off
	v_lshl_add_u64 v[144:145], v[144:145], 0, s[98:99]
	global_load_dword v130, v[144:145], off
	v_lshl_add_u64 v[144:145], v[144:145], 0, s[98:99]
	global_load_dword v131, v[144:145], off
	v_lshl_add_u64 v[144:145], v[144:145], 0, s[98:99]
	global_load_dword v132, v[144:145], off
	v_lshl_add_u64 v[144:145], v[144:145], 0, s[98:99]
	global_load_dword v133, v[144:145], off
	v_lshl_add_u64 v[144:145], v[144:145], 0, s[98:99]
	global_load_dword v134, v[144:145], off
	v_lshl_add_u64 v[144:145], v[144:145], 0, s[98:99]
	global_load_dword v135, v[144:145], off
	v_lshl_add_u64 v[144:145], v[144:145], 0, s[98:99]
	global_load_dword v136, v[144:145], off
	v_lshl_add_u64 v[144:145], v[144:145], 0, s[98:99]
	global_load_dword v137, v[144:145], off
	v_lshl_add_u64 v[144:145], v[144:145], 0, s[98:99]
	global_load_dword v138, v[144:145], off
	v_lshl_add_u64 v[144:145], v[144:145], 0, s[98:99]
	global_load_dword v139, v[144:145], off
	v_lshl_add_u64 v[144:145], v[144:145], 0, s[98:99]
	global_load_dword v140, v[144:145], off
	v_lshl_add_u64 v[144:145], v[144:145], 0, s[98:99]
	global_load_dword v141, v[144:145], off
	v_lshl_add_u64 v[144:145], v[144:145], 0, s[98:99]
	global_load_dword v142, v[144:145], off
	v_lshl_add_u64 v[144:145], v[144:145], 0, s[98:99]
	global_load_dword v143, v[144:145], off
	s_and_saveexec_b64 s[2:3], vcc
	s_cbranch_execz .LBB0_558
	v_lshl_or_b32 v10, s18, 8, v5
	s_load_dwordx2 s[14:15], s[0:1], 0x8
	s_load_dwordx2 s[12:13], s[0:1], 0x18
	v_ashrrev_i32_e32 v15, 8, v176
	v_lshl_or_b32 v12, v15, 10, v10
	v_ashrrev_i32_e32 v13, 31, v12
	s_mov_b64 s[10:11], 0x2000
	s_waitcnt lgkmcnt(0)
	v_lshl_add_u64 v[12:13], v[12:13], 2, s[14:15]
	global_load_dword v56, v[12:13], off
	v_lshl_add_u64 v[12:13], v[12:13], 0, s[10:11]
	global_load_dword v57, v[12:13], off
	v_lshl_add_u64 v[12:13], v[12:13], 0, s[10:11]
	global_load_dword v58, v[12:13], off
	v_lshl_add_u64 v[12:13], v[12:13], 0, s[10:11]
	global_load_dword v59, v[12:13], off
	v_lshl_add_u64 v[12:13], v[12:13], 0, s[10:11]
	global_load_dword v60, v[12:13], off
	v_lshl_add_u64 v[12:13], v[12:13], 0, s[10:11]
	global_load_dword v61, v[12:13], off
	v_lshl_add_u64 v[12:13], v[12:13], 0, s[10:11]
	global_load_dword v62, v[12:13], off
	v_lshl_add_u64 v[12:13], v[12:13], 0, s[10:11]
	global_load_dword v63, v[12:13], off
	v_lshl_add_u64 v[12:13], v[12:13], 0, s[10:11]
	global_load_dword v64, v[12:13], off
	v_lshl_add_u64 v[12:13], v[12:13], 0, s[10:11]
	global_load_dword v65, v[12:13], off
	v_lshl_add_u64 v[12:13], v[12:13], 0, s[10:11]
	global_load_dword v66, v[12:13], off
	v_lshl_add_u64 v[12:13], v[12:13], 0, s[10:11]
	global_load_dword v67, v[12:13], off
	v_lshl_add_u64 v[12:13], v[12:13], 0, s[10:11]
	global_load_dword v68, v[12:13], off
	v_lshl_add_u64 v[12:13], v[12:13], 0, s[10:11]
	global_load_dword v69, v[12:13], off
	v_lshl_add_u64 v[12:13], v[12:13], 0, s[10:11]
	global_load_dword v70, v[12:13], off
	v_lshl_add_u64 v[12:13], v[12:13], 0, s[10:11]
	global_load_dword v71, v[12:13], off
	s_movk_i32 s10, 0x100
	v_cmp_gt_u32_e64 s[10:11], s10, v176
	s_and_saveexec_b64 s[14:15], s[10:11]
	v_lshlrev_b32_e32 v192, 2, v10
	v_lshl_add_u64 v[12:13], s[12:13], 0, v[192:193]
	global_load_dword v72, v[12:13], off
	s_or_b64 exec, exec, s[14:15]
	s_waitcnt vmcnt(0)
	v_mul_f32_e32 v13, 0xbfb8aa3b, v56
	v_exp_f32_e32 v13, v13
	s_nop 0
	v_add_f32_e32 v13, 1.0, v13
	v_rcp_f32_e32 v13, v13
	s_nop 0
	v_mul_f32_e32 v12, v56, v13
	ds_write_b32 v52, v12
	v_mul_f32_e32 v13, 0xbfb8aa3b, v57
	v_exp_f32_e32 v13, v13
	s_nop 0
	v_add_f32_e32 v13, 1.0, v13
	v_rcp_f32_e32 v13, v13
	s_nop 0
	v_mul_f32_e32 v12, v57, v13
	ds_write_b32 v52, v12 offset:2048
	v_mul_f32_e32 v13, 0xbfb8aa3b, v58
	v_exp_f32_e32 v13, v13
	s_nop 0
	v_add_f32_e32 v13, 1.0, v13
	v_rcp_f32_e32 v13, v13
	s_nop 0
	v_mul_f32_e32 v12, v58, v13
	ds_write_b32 v52, v12 offset:4096
	v_mul_f32_e32 v13, 0xbfb8aa3b, v59
	v_exp_f32_e32 v13, v13
	s_nop 0
	v_add_f32_e32 v13, 1.0, v13
	v_rcp_f32_e32 v13, v13
	s_nop 0
	v_mul_f32_e32 v12, v59, v13
	ds_write_b32 v52, v12 offset:6144
	v_mul_f32_e32 v13, 0xbfb8aa3b, v60
	v_exp_f32_e32 v13, v13
	s_nop 0
	v_add_f32_e32 v13, 1.0, v13
	v_rcp_f32_e32 v13, v13
	s_nop 0
	v_mul_f32_e32 v12, v60, v13
	ds_write_b32 v52, v12 offset:8192
	v_mul_f32_e32 v13, 0xbfb8aa3b, v61
	v_exp_f32_e32 v13, v13
	s_nop 0
	v_add_f32_e32 v13, 1.0, v13
	v_rcp_f32_e32 v13, v13
	s_nop 0
	v_mul_f32_e32 v12, v61, v13
	ds_write_b32 v52, v12 offset:10240
	v_mul_f32_e32 v13, 0xbfb8aa3b, v62
	v_exp_f32_e32 v13, v13
	s_nop 0
	v_add_f32_e32 v13, 1.0, v13
	v_rcp_f32_e32 v13, v13
	s_nop 0
	v_mul_f32_e32 v12, v62, v13
	ds_write_b32 v52, v12 offset:12288
	v_mul_f32_e32 v13, 0xbfb8aa3b, v63
	v_exp_f32_e32 v13, v13
	s_nop 0
	v_add_f32_e32 v13, 1.0, v13
	v_rcp_f32_e32 v13, v13
	s_nop 0
	v_mul_f32_e32 v12, v63, v13
	ds_write_b32 v52, v12 offset:14336
	v_mul_f32_e32 v13, 0xbfb8aa3b, v64
	v_exp_f32_e32 v13, v13
	s_nop 0
	v_add_f32_e32 v13, 1.0, v13
	v_rcp_f32_e32 v13, v13
	s_nop 0
	v_mul_f32_e32 v12, v64, v13
	ds_write_b32 v52, v12 offset:16384
	v_mul_f32_e32 v13, 0xbfb8aa3b, v65
	v_exp_f32_e32 v13, v13
	s_nop 0
	v_add_f32_e32 v13, 1.0, v13
	v_rcp_f32_e32 v13, v13
	s_nop 0
	v_mul_f32_e32 v12, v65, v13
	ds_write_b32 v52, v12 offset:18432
	v_mul_f32_e32 v13, 0xbfb8aa3b, v66
	v_exp_f32_e32 v13, v13
	s_nop 0
	v_add_f32_e32 v13, 1.0, v13
	v_rcp_f32_e32 v13, v13
	s_nop 0
	v_mul_f32_e32 v12, v66, v13
	ds_write_b32 v52, v12 offset:20480
	v_mul_f32_e32 v13, 0xbfb8aa3b, v67
	v_exp_f32_e32 v13, v13
	s_nop 0
	v_add_f32_e32 v13, 1.0, v13
	v_rcp_f32_e32 v13, v13
	s_nop 0
	v_mul_f32_e32 v12, v67, v13
	ds_write_b32 v52, v12 offset:22528
	v_mul_f32_e32 v13, 0xbfb8aa3b, v68
	v_exp_f32_e32 v13, v13
	s_nop 0
	v_add_f32_e32 v13, 1.0, v13
	v_rcp_f32_e32 v13, v13
	s_nop 0
	v_mul_f32_e32 v12, v68, v13
	ds_write_b32 v52, v12 offset:24576
	v_mul_f32_e32 v13, 0xbfb8aa3b, v69
	v_exp_f32_e32 v13, v13
	s_nop 0
	v_add_f32_e32 v13, 1.0, v13
	v_rcp_f32_e32 v13, v13
	s_nop 0
	v_mul_f32_e32 v12, v69, v13
	ds_write_b32 v52, v12 offset:26624
	v_mul_f32_e32 v13, 0xbfb8aa3b, v70
	v_exp_f32_e32 v13, v13
	s_nop 0
	v_add_f32_e32 v13, 1.0, v13
	v_rcp_f32_e32 v13, v13
	s_nop 0
	v_mul_f32_e32 v12, v70, v13
	ds_write_b32 v52, v12 offset:28672
	v_mul_f32_e32 v13, 0xbfb8aa3b, v71
	v_exp_f32_e32 v13, v13
	s_nop 0
	v_add_f32_e32 v13, 1.0, v13
	v_rcp_f32_e32 v13, v13
	s_nop 0
	v_mul_f32_e32 v12, v71, v13
	ds_write_b32 v52, v12 offset:30720
	s_and_saveexec_b64 s[14:15], s[10:11]
	v_mul_f32_e32 v13, 0xbfb8aa3b, v72
	v_exp_f32_e32 v13, v13
	s_nop 0
	v_add_f32_e32 v13, 1.0, v13
	v_rcp_f32_e32 v13, v13
	s_nop 0
	v_mul_f32_e32 v12, v72, v13
	ds_write_b32 v52, v12 offset:32768
	s_or_b64 exec, exec, s[14:15]
.LBB0_558:
	s_or_b64 exec, exec, s[2:3]
	s_and_b32 s2, s22, 3
	s_lshl_b32 s14, s2, 8
	s_ashr_i32 s2, s23, 2
	s_mul_hi_i32 s3, s2, 0x2aaaaaab
	s_lshr_b32 s10, s3, 31
	s_lshr_b32 s3, s3, 3
	s_add_i32 s3, s3, s10
	s_mul_i32 s3, s3, 48
	s_sub_i32 s12, s2, s3
	s_mul_hi_i32 s2, s23, 0x2aaaaaab
	s_lshr_b32 s3, s2, 31
	s_ashr_i32 s2, s2, 5
	s_add_i32 s2, s2, s3
	s_ashr_i32 s3, s2, 31
	s_lshl_b64 s[10:11], s[2:3], 10
	s_lshl_b32 s12, s12, 7
	s_ashr_i32 s13, s12, 31
	s_or_b32 s10, s10, s14
	v_lshl_add_u64 v[10:11], s[10:11], 0, v[0:1]
	s_lshl_b64 s[10:11], s[12:13], 2
	v_mov_b64_e32 v[12:13], s[10:11]
	v_mad_u64_u32 v[12:13], s[10:11], v10, s67, v[12:13]
	v_mad_i32_i24 v13, v11, s67, v13
	v_mov_b32_e32 v54, 0
	v_lshl_add_u64 v[18:19], v[8:9], 0, v[12:13]
	s_mov_b32 s3, -4
	v_mov_b32_e32 v55, v3
	v_mov_b32_e32 v10, 0
	v_mov_b32_e32 v11, v54
	v_mov_b32_e32 v12, 0
	v_mov_b32_e32 v13, v54
	v_mov_b32_e32 v14, 0
	v_mov_b32_e32 v15, v54
	v_mov_b32_e32 v16, 0
	v_mov_b32_e32 v17, v54
	v_mov_b32_e32 v20, 0
	v_mov_b32_e32 v21, v54
	v_mov_b32_e32 v22, 0
	v_mov_b32_e32 v23, v54
	s_waitcnt vmcnt(1)
	v_mov_b32_e32 v24, 0
	v_mov_b32_e32 v25, v54
	v_mov_b32_e32 v26, 0
	v_mov_b32_e32 v27, v54
	s_waitcnt vmcnt(0)
	v_mov_b32_e32 v28, 0
	v_mov_b32_e32 v29, v54
	v_mov_b32_e32 v30, 0
	v_mov_b32_e32 v31, v54
	v_mov_b32_e32 v32, 0
	v_mov_b32_e32 v33, v54
	v_mov_b32_e32 v34, 0
	v_mov_b32_e32 v35, v54
	v_mov_b32_e32 v36, 0
	v_mov_b32_e32 v37, v54
	v_mov_b32_e32 v38, 0
	v_mov_b32_e32 v39, v54
	v_mov_b32_e32 v40, 0
	v_mov_b32_e32 v41, v54
	v_mov_b32_e32 v42, 0
	v_mov_b32_e32 v43, v54
	s_waitcnt lgkmcnt(0)
	s_barrier
	s_waitcnt vmcnt(0)
.LBB0_559:
	ds_read_b128 v[56:59], v55
	ds_read_b128 v[60:63], v55 offset:1024
	ds_read_b128 v[64:67], v55 offset:2048
	ds_read_b128 v[68:71], v55 offset:3072
	s_waitcnt lgkmcnt(3)
	v_fmac_f32_e32 v54, v80, v56
	v_fmac_f32_e32 v54, v81, v57
	v_fmac_f32_e32 v54, v82, v58
	v_fmac_f32_e32 v54, v83, v59
	ds_read_b128 v[56:59], v55 offset:4096
	s_waitcnt lgkmcnt(3)
	v_fmac_f32_e32 v43, v80, v60
	v_fmac_f32_e32 v43, v81, v61
	v_fmac_f32_e32 v43, v82, v62
	v_fmac_f32_e32 v43, v83, v63
	ds_read_b128 v[60:63], v55 offset:5120
	s_waitcnt lgkmcnt(3)
	v_fmac_f32_e32 v42, v80, v64
	v_fmac_f32_e32 v42, v81, v65
	v_fmac_f32_e32 v42, v82, v66
	v_fmac_f32_e32 v42, v83, v67
	ds_read_b128 v[64:67], v55 offset:6144
	s_waitcnt lgkmcnt(3)
	v_fmac_f32_e32 v41, v80, v68
	v_fmac_f32_e32 v41, v81, v69
	v_fmac_f32_e32 v41, v82, v70
	v_fmac_f32_e32 v41, v83, v71
	ds_read_b128 v[68:71], v55 offset:7168
	s_waitcnt lgkmcnt(3)
	v_fmac_f32_e32 v40, v80, v56
	v_fmac_f32_e32 v40, v81, v57
	v_fmac_f32_e32 v40, v82, v58
	v_fmac_f32_e32 v40, v83, v59
	ds_read_b128 v[56:59], v55 offset:8192
	s_waitcnt lgkmcnt(3)
	v_fmac_f32_e32 v39, v80, v60
	v_fmac_f32_e32 v39, v81, v61
	v_fmac_f32_e32 v39, v82, v62
	v_fmac_f32_e32 v39, v83, v63
	ds_read_b128 v[60:63], v55 offset:9216
	s_waitcnt lgkmcnt(3)
	v_fmac_f32_e32 v38, v80, v64
	v_fmac_f32_e32 v38, v81, v65
	v_fmac_f32_e32 v38, v82, v66
	v_fmac_f32_e32 v38, v83, v67
	ds_read_b128 v[64:67], v55 offset:10240
	s_waitcnt lgkmcnt(3)
	v_fmac_f32_e32 v37, v80, v68
	v_fmac_f32_e32 v37, v81, v69
	v_fmac_f32_e32 v37, v82, v70
	v_fmac_f32_e32 v37, v83, v71
	ds_read_b128 v[68:71], v55 offset:11264
	s_waitcnt lgkmcnt(3)
	v_fmac_f32_e32 v36, v80, v56
	v_fmac_f32_e32 v36, v81, v57
	v_fmac_f32_e32 v36, v82, v58
	v_fmac_f32_e32 v36, v83, v59
	ds_read_b128 v[56:59], v55 offset:12288
	s_waitcnt lgkmcnt(3)
	v_fmac_f32_e32 v35, v80, v60
	v_fmac_f32_e32 v35, v81, v61
	v_fmac_f32_e32 v35, v82, v62
	v_fmac_f32_e32 v35, v83, v63
	ds_read_b128 v[60:63], v55 offset:13312
	s_waitcnt lgkmcnt(3)
	v_fmac_f32_e32 v34, v80, v64
	v_fmac_f32_e32 v34, v81, v65
	v_fmac_f32_e32 v34, v82, v66
	v_fmac_f32_e32 v34, v83, v67
	ds_read_b128 v[64:67], v55 offset:14336
	s_waitcnt lgkmcnt(3)
	v_fmac_f32_e32 v33, v80, v68
	v_fmac_f32_e32 v33, v81, v69
	v_fmac_f32_e32 v33, v82, v70
	v_fmac_f32_e32 v33, v83, v71
	ds_read_b128 v[68:71], v55 offset:15360
	s_waitcnt lgkmcnt(3)
	v_fmac_f32_e32 v32, v80, v56
	v_fmac_f32_e32 v32, v81, v57
	v_fmac_f32_e32 v32, v82, v58
	v_fmac_f32_e32 v32, v83, v59
	ds_read_b128 v[56:59], v55 offset:16384
	s_waitcnt lgkmcnt(3)
	v_fmac_f32_e32 v31, v80, v60
	v_fmac_f32_e32 v31, v81, v61
	v_fmac_f32_e32 v31, v82, v62
	v_fmac_f32_e32 v31, v83, v63
	ds_read_b128 v[60:63], v55 offset:17408
	s_waitcnt lgkmcnt(3)
	v_fmac_f32_e32 v30, v80, v64
	v_fmac_f32_e32 v30, v81, v65
	v_fmac_f32_e32 v30, v82, v66
	v_fmac_f32_e32 v30, v83, v67
	ds_read_b128 v[64:67], v55 offset:18432
	s_waitcnt lgkmcnt(3)
	v_fmac_f32_e32 v29, v80, v68
	v_fmac_f32_e32 v29, v81, v69
	v_fmac_f32_e32 v29, v82, v70
	v_fmac_f32_e32 v29, v83, v71
	ds_read_b128 v[68:71], v55 offset:19456
	s_waitcnt lgkmcnt(3)
	v_fmac_f32_e32 v28, v80, v56
	v_fmac_f32_e32 v28, v81, v57
	v_fmac_f32_e32 v28, v82, v58
	v_fmac_f32_e32 v28, v83, v59
	ds_read_b128 v[56:59], v55 offset:20480
	s_waitcnt lgkmcnt(3)
	v_fmac_f32_e32 v27, v80, v60
	v_fmac_f32_e32 v27, v81, v61
	v_fmac_f32_e32 v27, v82, v62
	v_fmac_f32_e32 v27, v83, v63
	ds_read_b128 v[60:63], v55 offset:21504
	s_waitcnt lgkmcnt(3)
	v_fmac_f32_e32 v26, v80, v64
	v_fmac_f32_e32 v26, v81, v65
	v_fmac_f32_e32 v26, v82, v66
	v_fmac_f32_e32 v26, v83, v67
	ds_read_b128 v[64:67], v55 offset:22528
	s_waitcnt lgkmcnt(3)
	v_fmac_f32_e32 v25, v80, v68
	v_fmac_f32_e32 v25, v81, v69
	v_fmac_f32_e32 v25, v82, v70
	v_fmac_f32_e32 v25, v83, v71
	ds_read_b128 v[68:71], v55 offset:23552
	s_waitcnt lgkmcnt(3)
	v_fmac_f32_e32 v24, v80, v56
	v_fmac_f32_e32 v24, v81, v57
	v_fmac_f32_e32 v24, v82, v58
	v_fmac_f32_e32 v24, v83, v59
	ds_read_b128 v[56:59], v55 offset:24576
	s_waitcnt lgkmcnt(3)
	v_fmac_f32_e32 v23, v80, v60
	v_fmac_f32_e32 v23, v81, v61
	v_fmac_f32_e32 v23, v82, v62
	v_fmac_f32_e32 v23, v83, v63
	ds_read_b128 v[60:63], v55 offset:25600
	s_waitcnt lgkmcnt(3)
	v_fmac_f32_e32 v22, v80, v64
	v_fmac_f32_e32 v22, v81, v65
	v_fmac_f32_e32 v22, v82, v66
	v_fmac_f32_e32 v22, v83, v67
	ds_read_b128 v[64:67], v55 offset:26624
	s_waitcnt lgkmcnt(3)
	v_fmac_f32_e32 v21, v80, v68
	v_fmac_f32_e32 v21, v81, v69
	v_fmac_f32_e32 v21, v82, v70
	v_fmac_f32_e32 v21, v83, v71
	ds_read_b128 v[68:71], v55 offset:27648
	s_waitcnt lgkmcnt(3)
	v_fmac_f32_e32 v20, v80, v56
	v_fmac_f32_e32 v20, v81, v57
	v_fmac_f32_e32 v20, v82, v58
	v_fmac_f32_e32 v20, v83, v59
	ds_read_b128 v[56:59], v55 offset:28672
	s_waitcnt lgkmcnt(3)
	v_fmac_f32_e32 v17, v80, v60
	v_fmac_f32_e32 v17, v81, v61
	v_fmac_f32_e32 v17, v82, v62
	v_fmac_f32_e32 v17, v83, v63
	ds_read_b128 v[60:63], v55 offset:29696
	s_waitcnt lgkmcnt(3)
	v_fmac_f32_e32 v16, v80, v64
	v_fmac_f32_e32 v16, v81, v65
	v_fmac_f32_e32 v16, v82, v66
	v_fmac_f32_e32 v16, v83, v67
	ds_read_b128 v[64:67], v55 offset:30720
	s_waitcnt lgkmcnt(3)
	v_fmac_f32_e32 v15, v80, v68
	v_fmac_f32_e32 v15, v81, v69
	v_fmac_f32_e32 v15, v82, v70
	v_fmac_f32_e32 v15, v83, v71
	ds_read_b128 v[68:71], v55 offset:31744
	s_waitcnt lgkmcnt(3)
	v_fmac_f32_e32 v14, v80, v56
	v_fmac_f32_e32 v14, v81, v57
	v_fmac_f32_e32 v14, v82, v58
	v_fmac_f32_e32 v14, v83, v59
	ds_read_b128 v[56:59], v55 offset:32768
	s_waitcnt lgkmcnt(3)
	v_fmac_f32_e32 v13, v80, v60
	v_fmac_f32_e32 v13, v81, v61
	v_fmac_f32_e32 v13, v82, v62
	v_fmac_f32_e32 v13, v83, v63
	ds_read_b128 v[60:63], v55 offset:16
	s_waitcnt lgkmcnt(3)
	v_fmac_f32_e32 v12, v80, v64
	v_fmac_f32_e32 v12, v81, v65
	v_fmac_f32_e32 v12, v82, v66
	v_fmac_f32_e32 v12, v83, v67
	ds_read_b128 v[64:67], v55 offset:1040
	s_waitcnt lgkmcnt(3)
	v_fmac_f32_e32 v11, v80, v68
	v_fmac_f32_e32 v11, v81, v69
	v_fmac_f32_e32 v11, v82, v70
	v_fmac_f32_e32 v11, v83, v71
	ds_read_b128 v[68:71], v55 offset:2064
	s_waitcnt lgkmcnt(3)
	v_fmac_f32_e32 v10, v80, v56
	v_fmac_f32_e32 v10, v81, v57
	v_fmac_f32_e32 v10, v82, v58
	v_fmac_f32_e32 v10, v83, v59
	ds_read_b128 v[56:59], v55 offset:3088
	s_waitcnt lgkmcnt(3)
	v_fmac_f32_e32 v54, v84, v60
	v_fmac_f32_e32 v54, v85, v61
	v_fmac_f32_e32 v54, v86, v62
	v_fmac_f32_e32 v54, v87, v63
	ds_read_b128 v[60:63], v55 offset:4112
	s_waitcnt lgkmcnt(3)
	v_fmac_f32_e32 v43, v84, v64
	v_fmac_f32_e32 v43, v85, v65
	v_fmac_f32_e32 v43, v86, v66
	v_fmac_f32_e32 v43, v87, v67
	ds_read_b128 v[64:67], v55 offset:5136
	s_waitcnt lgkmcnt(3)
	v_fmac_f32_e32 v42, v84, v68
	v_fmac_f32_e32 v42, v85, v69
	v_fmac_f32_e32 v42, v86, v70
	v_fmac_f32_e32 v42, v87, v71
	ds_read_b128 v[68:71], v55 offset:6160
	s_waitcnt lgkmcnt(3)
	v_fmac_f32_e32 v41, v84, v56
	v_fmac_f32_e32 v41, v85, v57
	v_fmac_f32_e32 v41, v86, v58
	v_fmac_f32_e32 v41, v87, v59
	ds_read_b128 v[56:59], v55 offset:7184
	s_waitcnt lgkmcnt(3)
	v_fmac_f32_e32 v40, v84, v60
	v_fmac_f32_e32 v40, v85, v61
	v_fmac_f32_e32 v40, v86, v62
	v_fmac_f32_e32 v40, v87, v63
	ds_read_b128 v[60:63], v55 offset:8208
	s_waitcnt lgkmcnt(3)
	v_fmac_f32_e32 v39, v84, v64
	v_fmac_f32_e32 v39, v85, v65
	v_fmac_f32_e32 v39, v86, v66
	v_fmac_f32_e32 v39, v87, v67
	ds_read_b128 v[64:67], v55 offset:9232
	s_waitcnt lgkmcnt(3)
	v_fmac_f32_e32 v38, v84, v68
	v_fmac_f32_e32 v38, v85, v69
	v_fmac_f32_e32 v38, v86, v70
	v_fmac_f32_e32 v38, v87, v71
	ds_read_b128 v[68:71], v55 offset:10256
	s_waitcnt lgkmcnt(3)
	v_fmac_f32_e32 v37, v84, v56
	v_fmac_f32_e32 v37, v85, v57
	v_fmac_f32_e32 v37, v86, v58
	v_fmac_f32_e32 v37, v87, v59
	ds_read_b128 v[56:59], v55 offset:11280
	s_waitcnt lgkmcnt(3)
	v_fmac_f32_e32 v36, v84, v60
	v_fmac_f32_e32 v36, v85, v61
	v_fmac_f32_e32 v36, v86, v62
	v_fmac_f32_e32 v36, v87, v63
	ds_read_b128 v[60:63], v55 offset:12304
	s_waitcnt lgkmcnt(3)
	v_fmac_f32_e32 v35, v84, v64
	v_fmac_f32_e32 v35, v85, v65
	v_fmac_f32_e32 v35, v86, v66
	v_fmac_f32_e32 v35, v87, v67
	ds_read_b128 v[64:67], v55 offset:13328
	s_waitcnt lgkmcnt(3)
	v_fmac_f32_e32 v34, v84, v68
	v_fmac_f32_e32 v34, v85, v69
	v_fmac_f32_e32 v34, v86, v70
	v_fmac_f32_e32 v34, v87, v71
	ds_read_b128 v[68:71], v55 offset:14352
	s_waitcnt lgkmcnt(3)
	v_fmac_f32_e32 v33, v84, v56
	v_fmac_f32_e32 v33, v85, v57
	v_fmac_f32_e32 v33, v86, v58
	v_fmac_f32_e32 v33, v87, v59
	ds_read_b128 v[56:59], v55 offset:15376
	s_waitcnt lgkmcnt(3)
	v_fmac_f32_e32 v32, v84, v60
	v_fmac_f32_e32 v32, v85, v61
	v_fmac_f32_e32 v32, v86, v62
	v_fmac_f32_e32 v32, v87, v63
	ds_read_b128 v[60:63], v55 offset:16400
	s_waitcnt lgkmcnt(3)
	v_fmac_f32_e32 v31, v84, v64
	v_fmac_f32_e32 v31, v85, v65
	v_fmac_f32_e32 v31, v86, v66
	v_fmac_f32_e32 v31, v87, v67
	ds_read_b128 v[64:67], v55 offset:17424
	s_waitcnt lgkmcnt(3)
	v_fmac_f32_e32 v30, v84, v68
	v_fmac_f32_e32 v30, v85, v69
	v_fmac_f32_e32 v30, v86, v70
	v_fmac_f32_e32 v30, v87, v71
	ds_read_b128 v[68:71], v55 offset:18448
	s_waitcnt lgkmcnt(3)
	v_fmac_f32_e32 v29, v84, v56
	v_fmac_f32_e32 v29, v85, v57
	v_fmac_f32_e32 v29, v86, v58
	v_fmac_f32_e32 v29, v87, v59
	ds_read_b128 v[56:59], v55 offset:19472
	s_waitcnt lgkmcnt(3)
	v_fmac_f32_e32 v28, v84, v60
	v_fmac_f32_e32 v28, v85, v61
	v_fmac_f32_e32 v28, v86, v62
	v_fmac_f32_e32 v28, v87, v63
	ds_read_b128 v[60:63], v55 offset:20496
	s_waitcnt lgkmcnt(3)
	v_fmac_f32_e32 v27, v84, v64
	v_fmac_f32_e32 v27, v85, v65
	v_fmac_f32_e32 v27, v86, v66
	v_fmac_f32_e32 v27, v87, v67
	ds_read_b128 v[64:67], v55 offset:21520
	s_waitcnt lgkmcnt(3)
	v_fmac_f32_e32 v26, v84, v68
	v_fmac_f32_e32 v26, v85, v69
	v_fmac_f32_e32 v26, v86, v70
	v_fmac_f32_e32 v26, v87, v71
	ds_read_b128 v[68:71], v55 offset:22544
	s_waitcnt lgkmcnt(3)
	v_fmac_f32_e32 v25, v84, v56
	v_fmac_f32_e32 v25, v85, v57
	v_fmac_f32_e32 v25, v86, v58
	v_fmac_f32_e32 v25, v87, v59
	ds_read_b128 v[56:59], v55 offset:23568
	s_waitcnt lgkmcnt(3)
	v_fmac_f32_e32 v24, v84, v60
	v_fmac_f32_e32 v24, v85, v61
	v_fmac_f32_e32 v24, v86, v62
	v_fmac_f32_e32 v24, v87, v63
	ds_read_b128 v[60:63], v55 offset:24592
	s_waitcnt lgkmcnt(3)
	v_fmac_f32_e32 v23, v84, v64
	v_fmac_f32_e32 v23, v85, v65
	v_fmac_f32_e32 v23, v86, v66
	v_fmac_f32_e32 v23, v87, v67
	ds_read_b128 v[64:67], v55 offset:25616
	s_waitcnt lgkmcnt(3)
	v_fmac_f32_e32 v22, v84, v68
	v_fmac_f32_e32 v22, v85, v69
	v_fmac_f32_e32 v22, v86, v70
	v_fmac_f32_e32 v22, v87, v71
	ds_read_b128 v[68:71], v55 offset:26640
	s_waitcnt lgkmcnt(3)
	v_fmac_f32_e32 v21, v84, v56
	v_fmac_f32_e32 v21, v85, v57
	v_fmac_f32_e32 v21, v86, v58
	v_fmac_f32_e32 v21, v87, v59
	ds_read_b128 v[56:59], v55 offset:27664
	s_waitcnt lgkmcnt(3)
	v_fmac_f32_e32 v20, v84, v60
	v_fmac_f32_e32 v20, v85, v61
	v_fmac_f32_e32 v20, v86, v62
	v_fmac_f32_e32 v20, v87, v63
	ds_read_b128 v[60:63], v55 offset:28688
	s_waitcnt lgkmcnt(3)
	v_fmac_f32_e32 v17, v84, v64
	v_fmac_f32_e32 v17, v85, v65
	v_fmac_f32_e32 v17, v86, v66
	v_fmac_f32_e32 v17, v87, v67
	ds_read_b128 v[64:67], v55 offset:29712
	s_waitcnt lgkmcnt(3)
	v_fmac_f32_e32 v16, v84, v68
	v_fmac_f32_e32 v16, v85, v69
	v_fmac_f32_e32 v16, v86, v70
	v_fmac_f32_e32 v16, v87, v71
	ds_read_b128 v[68:71], v55 offset:30736
	s_waitcnt lgkmcnt(3)
	v_fmac_f32_e32 v15, v84, v56
	v_fmac_f32_e32 v15, v85, v57
	v_fmac_f32_e32 v15, v86, v58
	v_fmac_f32_e32 v15, v87, v59
	ds_read_b128 v[56:59], v55 offset:31760
	s_waitcnt lgkmcnt(3)
	v_fmac_f32_e32 v14, v84, v60
	v_fmac_f32_e32 v14, v85, v61
	v_fmac_f32_e32 v14, v86, v62
	v_fmac_f32_e32 v14, v87, v63
	ds_read_b128 v[60:63], v55 offset:32784
	s_waitcnt lgkmcnt(3)
	v_fmac_f32_e32 v13, v84, v64
	v_fmac_f32_e32 v13, v85, v65
	v_fmac_f32_e32 v13, v86, v66
	v_fmac_f32_e32 v13, v87, v67
	ds_read_b128 v[64:67], v55 offset:32
	s_waitcnt lgkmcnt(3)
	v_fmac_f32_e32 v12, v84, v68
	v_fmac_f32_e32 v12, v85, v69
	v_fmac_f32_e32 v12, v86, v70
	v_fmac_f32_e32 v12, v87, v71
	ds_read_b128 v[68:71], v55 offset:1056
	s_waitcnt lgkmcnt(3)
	v_fmac_f32_e32 v11, v84, v56
	v_fmac_f32_e32 v11, v85, v57
	v_fmac_f32_e32 v11, v86, v58
	v_fmac_f32_e32 v11, v87, v59
	ds_read_b128 v[56:59], v55 offset:2080
	s_waitcnt lgkmcnt(3)
	v_fmac_f32_e32 v10, v84, v60
	v_fmac_f32_e32 v10, v85, v61
	v_fmac_f32_e32 v10, v86, v62
	v_fmac_f32_e32 v10, v87, v63
	ds_read_b128 v[60:63], v55 offset:3104
	s_waitcnt lgkmcnt(3)
	v_fmac_f32_e32 v54, v88, v64
	v_fmac_f32_e32 v54, v89, v65
	v_fmac_f32_e32 v54, v90, v66
	v_fmac_f32_e32 v54, v91, v67
	ds_read_b128 v[64:67], v55 offset:4128
	s_waitcnt lgkmcnt(3)
	v_fmac_f32_e32 v43, v88, v68
	v_fmac_f32_e32 v43, v89, v69
	v_fmac_f32_e32 v43, v90, v70
	v_fmac_f32_e32 v43, v91, v71
	ds_read_b128 v[68:71], v55 offset:5152
	s_waitcnt lgkmcnt(3)
	v_fmac_f32_e32 v42, v88, v56
	v_fmac_f32_e32 v42, v89, v57
	v_fmac_f32_e32 v42, v90, v58
	v_fmac_f32_e32 v42, v91, v59
	ds_read_b128 v[56:59], v55 offset:6176
	s_waitcnt lgkmcnt(3)
	v_fmac_f32_e32 v41, v88, v60
	v_fmac_f32_e32 v41, v89, v61
	v_fmac_f32_e32 v41, v90, v62
	v_fmac_f32_e32 v41, v91, v63
	ds_read_b128 v[60:63], v55 offset:7200
	s_waitcnt lgkmcnt(3)
	v_fmac_f32_e32 v40, v88, v64
	v_fmac_f32_e32 v40, v89, v65
	v_fmac_f32_e32 v40, v90, v66
	v_fmac_f32_e32 v40, v91, v67
	ds_read_b128 v[64:67], v55 offset:8224
	s_waitcnt lgkmcnt(3)
	v_fmac_f32_e32 v39, v88, v68
	v_fmac_f32_e32 v39, v89, v69
	v_fmac_f32_e32 v39, v90, v70
	v_fmac_f32_e32 v39, v91, v71
	ds_read_b128 v[68:71], v55 offset:9248
	s_waitcnt lgkmcnt(3)
	v_fmac_f32_e32 v38, v88, v56
	v_fmac_f32_e32 v38, v89, v57
	v_fmac_f32_e32 v38, v90, v58
	v_fmac_f32_e32 v38, v91, v59
	ds_read_b128 v[56:59], v55 offset:10272
	s_waitcnt lgkmcnt(3)
	v_fmac_f32_e32 v37, v88, v60
	v_fmac_f32_e32 v37, v89, v61
	v_fmac_f32_e32 v37, v90, v62
	v_fmac_f32_e32 v37, v91, v63
	ds_read_b128 v[60:63], v55 offset:11296
	s_waitcnt lgkmcnt(3)
	v_fmac_f32_e32 v36, v88, v64
	v_fmac_f32_e32 v36, v89, v65
	v_fmac_f32_e32 v36, v90, v66
	v_fmac_f32_e32 v36, v91, v67
	ds_read_b128 v[64:67], v55 offset:12320
	s_waitcnt lgkmcnt(3)
	v_fmac_f32_e32 v35, v88, v68
	v_fmac_f32_e32 v35, v89, v69
	v_fmac_f32_e32 v35, v90, v70
	v_fmac_f32_e32 v35, v91, v71
	ds_read_b128 v[68:71], v55 offset:13344
	s_waitcnt lgkmcnt(3)
	v_fmac_f32_e32 v34, v88, v56
	v_fmac_f32_e32 v34, v89, v57
	v_fmac_f32_e32 v34, v90, v58
	v_fmac_f32_e32 v34, v91, v59
	ds_read_b128 v[56:59], v55 offset:14368
	s_waitcnt lgkmcnt(3)
	v_fmac_f32_e32 v33, v88, v60
	v_fmac_f32_e32 v33, v89, v61
	v_fmac_f32_e32 v33, v90, v62
	v_fmac_f32_e32 v33, v91, v63
	ds_read_b128 v[60:63], v55 offset:15392
	s_waitcnt lgkmcnt(3)
	v_fmac_f32_e32 v32, v88, v64
	v_fmac_f32_e32 v32, v89, v65
	v_fmac_f32_e32 v32, v90, v66
	v_fmac_f32_e32 v32, v91, v67
	ds_read_b128 v[64:67], v55 offset:16416
	s_waitcnt lgkmcnt(3)
	v_fmac_f32_e32 v31, v88, v68
	v_fmac_f32_e32 v31, v89, v69
	v_fmac_f32_e32 v31, v90, v70
	v_fmac_f32_e32 v31, v91, v71
	ds_read_b128 v[68:71], v55 offset:17440
	s_waitcnt lgkmcnt(3)
	v_fmac_f32_e32 v30, v88, v56
	v_fmac_f32_e32 v30, v89, v57
	v_fmac_f32_e32 v30, v90, v58
	v_fmac_f32_e32 v30, v91, v59
	ds_read_b128 v[56:59], v55 offset:18464
	s_waitcnt lgkmcnt(3)
	v_fmac_f32_e32 v29, v88, v60
	v_fmac_f32_e32 v29, v89, v61
	v_fmac_f32_e32 v29, v90, v62
	v_fmac_f32_e32 v29, v91, v63
	ds_read_b128 v[60:63], v55 offset:19488
	s_waitcnt lgkmcnt(3)
	v_fmac_f32_e32 v28, v88, v64
	v_fmac_f32_e32 v28, v89, v65
	v_fmac_f32_e32 v28, v90, v66
	v_fmac_f32_e32 v28, v91, v67
	ds_read_b128 v[64:67], v55 offset:20512
	s_waitcnt lgkmcnt(3)
	v_fmac_f32_e32 v27, v88, v68
	v_fmac_f32_e32 v27, v89, v69
	v_fmac_f32_e32 v27, v90, v70
	v_fmac_f32_e32 v27, v91, v71
	ds_read_b128 v[68:71], v55 offset:21536
	s_waitcnt lgkmcnt(3)
	v_fmac_f32_e32 v26, v88, v56
	v_fmac_f32_e32 v26, v89, v57
	v_fmac_f32_e32 v26, v90, v58
	v_fmac_f32_e32 v26, v91, v59
	ds_read_b128 v[56:59], v55 offset:22560
	s_waitcnt lgkmcnt(3)
	v_fmac_f32_e32 v25, v88, v60
	v_fmac_f32_e32 v25, v89, v61
	v_fmac_f32_e32 v25, v90, v62
	v_fmac_f32_e32 v25, v91, v63
	ds_read_b128 v[60:63], v55 offset:23584
	s_waitcnt lgkmcnt(3)
	v_fmac_f32_e32 v24, v88, v64
	v_fmac_f32_e32 v24, v89, v65
	v_fmac_f32_e32 v24, v90, v66
	v_fmac_f32_e32 v24, v91, v67
	ds_read_b128 v[64:67], v55 offset:24608
	s_waitcnt lgkmcnt(3)
	v_fmac_f32_e32 v23, v88, v68
	v_fmac_f32_e32 v23, v89, v69
	v_fmac_f32_e32 v23, v90, v70
	v_fmac_f32_e32 v23, v91, v71
	ds_read_b128 v[68:71], v55 offset:25632
	s_waitcnt lgkmcnt(3)
	v_fmac_f32_e32 v22, v88, v56
	v_fmac_f32_e32 v22, v89, v57
	v_fmac_f32_e32 v22, v90, v58
	v_fmac_f32_e32 v22, v91, v59
	ds_read_b128 v[56:59], v55 offset:26656
	s_waitcnt lgkmcnt(3)
	v_fmac_f32_e32 v21, v88, v60
	v_fmac_f32_e32 v21, v89, v61
	v_fmac_f32_e32 v21, v90, v62
	v_fmac_f32_e32 v21, v91, v63
	ds_read_b128 v[60:63], v55 offset:27680
	s_waitcnt lgkmcnt(3)
	v_fmac_f32_e32 v20, v88, v64
	v_fmac_f32_e32 v20, v89, v65
	v_fmac_f32_e32 v20, v90, v66
	v_fmac_f32_e32 v20, v91, v67
	ds_read_b128 v[64:67], v55 offset:28704
	s_waitcnt lgkmcnt(3)
	v_fmac_f32_e32 v17, v88, v68
	v_fmac_f32_e32 v17, v89, v69
	v_fmac_f32_e32 v17, v90, v70
	v_fmac_f32_e32 v17, v91, v71
	ds_read_b128 v[68:71], v55 offset:29728
	s_waitcnt lgkmcnt(3)
	v_fmac_f32_e32 v16, v88, v56
	v_fmac_f32_e32 v16, v89, v57
	v_fmac_f32_e32 v16, v90, v58
	v_fmac_f32_e32 v16, v91, v59
	ds_read_b128 v[56:59], v55 offset:30752
	s_waitcnt lgkmcnt(3)
	v_fmac_f32_e32 v15, v88, v60
	v_fmac_f32_e32 v15, v89, v61
	v_fmac_f32_e32 v15, v90, v62
	v_fmac_f32_e32 v15, v91, v63
	ds_read_b128 v[60:63], v55 offset:31776
	s_waitcnt lgkmcnt(3)
	v_fmac_f32_e32 v14, v88, v64
	v_fmac_f32_e32 v14, v89, v65
	v_fmac_f32_e32 v14, v90, v66
	v_fmac_f32_e32 v14, v91, v67
	ds_read_b128 v[64:67], v55 offset:32800
	s_waitcnt lgkmcnt(3)
	v_fmac_f32_e32 v13, v88, v68
	v_fmac_f32_e32 v13, v89, v69
	v_fmac_f32_e32 v13, v90, v70
	v_fmac_f32_e32 v13, v91, v71
	ds_read_b128 v[68:71], v55 offset:48
	s_waitcnt lgkmcnt(3)
	v_fmac_f32_e32 v12, v88, v56
	v_fmac_f32_e32 v12, v89, v57
	v_fmac_f32_e32 v12, v90, v58
	v_fmac_f32_e32 v12, v91, v59
	ds_read_b128 v[56:59], v55 offset:1072
	s_waitcnt lgkmcnt(3)
	v_fmac_f32_e32 v11, v88, v60
	v_fmac_f32_e32 v11, v89, v61
	v_fmac_f32_e32 v11, v90, v62
	v_fmac_f32_e32 v11, v91, v63
	ds_read_b128 v[60:63], v55 offset:2096
	s_waitcnt lgkmcnt(3)
	v_fmac_f32_e32 v10, v88, v64
	v_fmac_f32_e32 v10, v89, v65
	v_fmac_f32_e32 v10, v90, v66
	v_fmac_f32_e32 v10, v91, v67
	ds_read_b128 v[64:67], v55 offset:3120
	s_waitcnt lgkmcnt(3)
	v_fmac_f32_e32 v54, v92, v68
	v_fmac_f32_e32 v54, v93, v69
	v_fmac_f32_e32 v54, v94, v70
	v_fmac_f32_e32 v54, v95, v71
	ds_read_b128 v[68:71], v55 offset:4144
	s_waitcnt lgkmcnt(3)
	v_fmac_f32_e32 v43, v92, v56
	v_fmac_f32_e32 v43, v93, v57
	v_fmac_f32_e32 v43, v94, v58
	v_fmac_f32_e32 v43, v95, v59
	ds_read_b128 v[56:59], v55 offset:5168
	s_waitcnt lgkmcnt(3)
	v_fmac_f32_e32 v42, v92, v60
	v_fmac_f32_e32 v42, v93, v61
	v_fmac_f32_e32 v42, v94, v62
	v_fmac_f32_e32 v42, v95, v63
	ds_read_b128 v[60:63], v55 offset:6192
	s_waitcnt lgkmcnt(3)
	v_fmac_f32_e32 v41, v92, v64
	v_fmac_f32_e32 v41, v93, v65
	v_fmac_f32_e32 v41, v94, v66
	v_fmac_f32_e32 v41, v95, v67
	ds_read_b128 v[64:67], v55 offset:7216
	s_waitcnt lgkmcnt(3)
	v_fmac_f32_e32 v40, v92, v68
	v_fmac_f32_e32 v40, v93, v69
	v_fmac_f32_e32 v40, v94, v70
	v_fmac_f32_e32 v40, v95, v71
	ds_read_b128 v[68:71], v55 offset:8240
	s_waitcnt lgkmcnt(3)
	v_fmac_f32_e32 v39, v92, v56
	v_fmac_f32_e32 v39, v93, v57
	v_fmac_f32_e32 v39, v94, v58
	v_fmac_f32_e32 v39, v95, v59
	ds_read_b128 v[56:59], v55 offset:9264
	s_waitcnt lgkmcnt(3)
	v_fmac_f32_e32 v38, v92, v60
	v_fmac_f32_e32 v38, v93, v61
	v_fmac_f32_e32 v38, v94, v62
	v_fmac_f32_e32 v38, v95, v63
	ds_read_b128 v[60:63], v55 offset:10288
	s_waitcnt lgkmcnt(3)
	v_fmac_f32_e32 v37, v92, v64
	v_fmac_f32_e32 v37, v93, v65
	v_fmac_f32_e32 v37, v94, v66
	v_fmac_f32_e32 v37, v95, v67
	ds_read_b128 v[64:67], v55 offset:11312
	s_waitcnt lgkmcnt(3)
	v_fmac_f32_e32 v36, v92, v68
	v_fmac_f32_e32 v36, v93, v69
	v_fmac_f32_e32 v36, v94, v70
	v_fmac_f32_e32 v36, v95, v71
	ds_read_b128 v[68:71], v55 offset:12336
	s_waitcnt lgkmcnt(3)
	v_fmac_f32_e32 v35, v92, v56
	v_fmac_f32_e32 v35, v93, v57
	v_fmac_f32_e32 v35, v94, v58
	v_fmac_f32_e32 v35, v95, v59
	ds_read_b128 v[56:59], v55 offset:13360
	s_waitcnt lgkmcnt(3)
	v_fmac_f32_e32 v34, v92, v60
	v_fmac_f32_e32 v34, v93, v61
	v_fmac_f32_e32 v34, v94, v62
	v_fmac_f32_e32 v34, v95, v63
	ds_read_b128 v[60:63], v55 offset:14384
	s_waitcnt lgkmcnt(3)
	v_fmac_f32_e32 v33, v92, v64
	v_fmac_f32_e32 v33, v93, v65
	v_fmac_f32_e32 v33, v94, v66
	v_fmac_f32_e32 v33, v95, v67
	ds_read_b128 v[64:67], v55 offset:15408
	s_waitcnt lgkmcnt(3)
	v_fmac_f32_e32 v32, v92, v68
	v_fmac_f32_e32 v32, v93, v69
	v_fmac_f32_e32 v32, v94, v70
	v_fmac_f32_e32 v32, v95, v71
	ds_read_b128 v[68:71], v55 offset:16432
	s_waitcnt lgkmcnt(3)
	v_fmac_f32_e32 v31, v92, v56
	v_fmac_f32_e32 v31, v93, v57
	v_fmac_f32_e32 v31, v94, v58
	v_fmac_f32_e32 v31, v95, v59
	ds_read_b128 v[56:59], v55 offset:17456
	s_waitcnt lgkmcnt(3)
	v_fmac_f32_e32 v30, v92, v60
	v_fmac_f32_e32 v30, v93, v61
	v_fmac_f32_e32 v30, v94, v62
	v_fmac_f32_e32 v30, v95, v63
	ds_read_b128 v[60:63], v55 offset:18480
	s_waitcnt lgkmcnt(3)
	v_fmac_f32_e32 v29, v92, v64
	v_fmac_f32_e32 v29, v93, v65
	v_fmac_f32_e32 v29, v94, v66
	v_fmac_f32_e32 v29, v95, v67
	ds_read_b128 v[64:67], v55 offset:19504
	s_waitcnt lgkmcnt(3)
	v_fmac_f32_e32 v28, v92, v68
	v_fmac_f32_e32 v28, v93, v69
	v_fmac_f32_e32 v28, v94, v70
	v_fmac_f32_e32 v28, v95, v71
	ds_read_b128 v[68:71], v55 offset:20528
	s_waitcnt lgkmcnt(3)
	v_fmac_f32_e32 v27, v92, v56
	v_fmac_f32_e32 v27, v93, v57
	v_fmac_f32_e32 v27, v94, v58
	v_fmac_f32_e32 v27, v95, v59
	ds_read_b128 v[56:59], v55 offset:21552
	s_waitcnt lgkmcnt(3)
	v_fmac_f32_e32 v26, v92, v60
	v_fmac_f32_e32 v26, v93, v61
	v_fmac_f32_e32 v26, v94, v62
	v_fmac_f32_e32 v26, v95, v63
	ds_read_b128 v[60:63], v55 offset:22576
	s_waitcnt lgkmcnt(3)
	v_fmac_f32_e32 v25, v92, v64
	v_fmac_f32_e32 v25, v93, v65
	v_fmac_f32_e32 v25, v94, v66
	v_fmac_f32_e32 v25, v95, v67
	ds_read_b128 v[64:67], v55 offset:23600
	s_waitcnt lgkmcnt(3)
	v_fmac_f32_e32 v24, v92, v68
	v_fmac_f32_e32 v24, v93, v69
	v_fmac_f32_e32 v24, v94, v70
	v_fmac_f32_e32 v24, v95, v71
	ds_read_b128 v[68:71], v55 offset:24624
	s_waitcnt lgkmcnt(3)
	v_fmac_f32_e32 v23, v92, v56
	v_fmac_f32_e32 v23, v93, v57
	v_fmac_f32_e32 v23, v94, v58
	v_fmac_f32_e32 v23, v95, v59
	ds_read_b128 v[56:59], v55 offset:25648
	s_waitcnt lgkmcnt(3)
	v_fmac_f32_e32 v22, v92, v60
	v_fmac_f32_e32 v22, v93, v61
	v_fmac_f32_e32 v22, v94, v62
	v_fmac_f32_e32 v22, v95, v63
	ds_read_b128 v[60:63], v55 offset:26672
	s_waitcnt lgkmcnt(3)
	v_fmac_f32_e32 v21, v92, v64
	v_fmac_f32_e32 v21, v93, v65
	v_fmac_f32_e32 v21, v94, v66
	v_fmac_f32_e32 v21, v95, v67
	ds_read_b128 v[64:67], v55 offset:27696
	s_waitcnt lgkmcnt(3)
	v_fmac_f32_e32 v20, v92, v68
	v_fmac_f32_e32 v20, v93, v69
	v_fmac_f32_e32 v20, v94, v70
	v_fmac_f32_e32 v20, v95, v71
	ds_read_b128 v[68:71], v55 offset:28720
	s_waitcnt lgkmcnt(3)
	v_fmac_f32_e32 v17, v92, v56
	v_fmac_f32_e32 v17, v93, v57
	v_fmac_f32_e32 v17, v94, v58
	v_fmac_f32_e32 v17, v95, v59
	ds_read_b128 v[56:59], v55 offset:29744
	s_waitcnt lgkmcnt(3)
	v_fmac_f32_e32 v16, v92, v60
	v_fmac_f32_e32 v16, v93, v61
	v_fmac_f32_e32 v16, v94, v62
	v_fmac_f32_e32 v16, v95, v63
	ds_read_b128 v[60:63], v55 offset:30768
	s_waitcnt lgkmcnt(3)
	v_fmac_f32_e32 v15, v92, v64
	v_fmac_f32_e32 v15, v93, v65
	v_fmac_f32_e32 v15, v94, v66
	v_fmac_f32_e32 v15, v95, v67
	ds_read_b128 v[64:67], v55 offset:31792
	s_waitcnt lgkmcnt(3)
	v_fmac_f32_e32 v14, v92, v68
	v_fmac_f32_e32 v14, v93, v69
	v_fmac_f32_e32 v14, v94, v70
	v_fmac_f32_e32 v14, v95, v71
	ds_read_b128 v[68:71], v55 offset:32816
	s_waitcnt lgkmcnt(3)
	v_fmac_f32_e32 v13, v92, v56
	v_fmac_f32_e32 v13, v93, v57
	v_fmac_f32_e32 v13, v94, v58
	v_fmac_f32_e32 v13, v95, v59
	ds_read_b128 v[56:59], v55 offset:64
	s_waitcnt lgkmcnt(3)
	v_fmac_f32_e32 v12, v92, v60
	v_fmac_f32_e32 v12, v93, v61
	v_fmac_f32_e32 v12, v94, v62
	v_fmac_f32_e32 v12, v95, v63
	ds_read_b128 v[60:63], v55 offset:1088
	s_waitcnt lgkmcnt(3)
	v_fmac_f32_e32 v11, v92, v64
	v_fmac_f32_e32 v11, v93, v65
	v_fmac_f32_e32 v11, v94, v66
	v_fmac_f32_e32 v11, v95, v67
	ds_read_b128 v[64:67], v55 offset:2112
	s_waitcnt lgkmcnt(3)
	v_fmac_f32_e32 v10, v92, v68
	v_fmac_f32_e32 v10, v93, v69
	v_fmac_f32_e32 v10, v94, v70
	v_fmac_f32_e32 v10, v95, v71
	ds_read_b128 v[68:71], v55 offset:3136
	s_waitcnt lgkmcnt(3)
	v_fmac_f32_e32 v54, v96, v56
	v_fmac_f32_e32 v54, v97, v57
	v_fmac_f32_e32 v54, v98, v58
	v_fmac_f32_e32 v54, v99, v59
	ds_read_b128 v[56:59], v55 offset:4160
	s_waitcnt lgkmcnt(3)
	v_fmac_f32_e32 v43, v96, v60
	v_fmac_f32_e32 v43, v97, v61
	v_fmac_f32_e32 v43, v98, v62
	v_fmac_f32_e32 v43, v99, v63
	ds_read_b128 v[60:63], v55 offset:5184
	s_waitcnt lgkmcnt(3)
	v_fmac_f32_e32 v42, v96, v64
	v_fmac_f32_e32 v42, v97, v65
	v_fmac_f32_e32 v42, v98, v66
	v_fmac_f32_e32 v42, v99, v67
	ds_read_b128 v[64:67], v55 offset:6208
	s_waitcnt lgkmcnt(3)
	v_fmac_f32_e32 v41, v96, v68
	v_fmac_f32_e32 v41, v97, v69
	v_fmac_f32_e32 v41, v98, v70
	v_fmac_f32_e32 v41, v99, v71
	ds_read_b128 v[68:71], v55 offset:7232
	s_waitcnt lgkmcnt(3)
	v_fmac_f32_e32 v40, v96, v56
	v_fmac_f32_e32 v40, v97, v57
	v_fmac_f32_e32 v40, v98, v58
	v_fmac_f32_e32 v40, v99, v59
	ds_read_b128 v[56:59], v55 offset:8256
	s_waitcnt lgkmcnt(3)
	v_fmac_f32_e32 v39, v96, v60
	v_fmac_f32_e32 v39, v97, v61
	v_fmac_f32_e32 v39, v98, v62
	v_fmac_f32_e32 v39, v99, v63
	ds_read_b128 v[60:63], v55 offset:9280
	s_waitcnt lgkmcnt(3)
	v_fmac_f32_e32 v38, v96, v64
	v_fmac_f32_e32 v38, v97, v65
	v_fmac_f32_e32 v38, v98, v66
	v_fmac_f32_e32 v38, v99, v67
	ds_read_b128 v[64:67], v55 offset:10304
	s_waitcnt lgkmcnt(3)
	v_fmac_f32_e32 v37, v96, v68
	v_fmac_f32_e32 v37, v97, v69
	v_fmac_f32_e32 v37, v98, v70
	v_fmac_f32_e32 v37, v99, v71
	ds_read_b128 v[68:71], v55 offset:11328
	s_waitcnt lgkmcnt(3)
	v_fmac_f32_e32 v36, v96, v56
	v_fmac_f32_e32 v36, v97, v57
	v_fmac_f32_e32 v36, v98, v58
	v_fmac_f32_e32 v36, v99, v59
	ds_read_b128 v[56:59], v55 offset:12352
	s_waitcnt lgkmcnt(3)
	v_fmac_f32_e32 v35, v96, v60
	v_fmac_f32_e32 v35, v97, v61
	v_fmac_f32_e32 v35, v98, v62
	v_fmac_f32_e32 v35, v99, v63
	ds_read_b128 v[60:63], v55 offset:13376
	s_waitcnt lgkmcnt(3)
	v_fmac_f32_e32 v34, v96, v64
	v_fmac_f32_e32 v34, v97, v65
	v_fmac_f32_e32 v34, v98, v66
	v_fmac_f32_e32 v34, v99, v67
	ds_read_b128 v[64:67], v55 offset:14400
	s_waitcnt lgkmcnt(3)
	v_fmac_f32_e32 v33, v96, v68
	v_fmac_f32_e32 v33, v97, v69
	v_fmac_f32_e32 v33, v98, v70
	v_fmac_f32_e32 v33, v99, v71
	ds_read_b128 v[68:71], v55 offset:15424
	s_waitcnt lgkmcnt(3)
	v_fmac_f32_e32 v32, v96, v56
	v_fmac_f32_e32 v32, v97, v57
	v_fmac_f32_e32 v32, v98, v58
	v_fmac_f32_e32 v32, v99, v59
	ds_read_b128 v[56:59], v55 offset:16448
	s_waitcnt lgkmcnt(3)
	v_fmac_f32_e32 v31, v96, v60
	v_fmac_f32_e32 v31, v97, v61
	v_fmac_f32_e32 v31, v98, v62
	v_fmac_f32_e32 v31, v99, v63
	ds_read_b128 v[60:63], v55 offset:17472
	s_waitcnt lgkmcnt(3)
	v_fmac_f32_e32 v30, v96, v64
	v_fmac_f32_e32 v30, v97, v65
	v_fmac_f32_e32 v30, v98, v66
	v_fmac_f32_e32 v30, v99, v67
	ds_read_b128 v[64:67], v55 offset:18496
	s_waitcnt lgkmcnt(3)
	v_fmac_f32_e32 v29, v96, v68
	v_fmac_f32_e32 v29, v97, v69
	v_fmac_f32_e32 v29, v98, v70
	v_fmac_f32_e32 v29, v99, v71
	ds_read_b128 v[68:71], v55 offset:19520
	s_waitcnt lgkmcnt(3)
	v_fmac_f32_e32 v28, v96, v56
	v_fmac_f32_e32 v28, v97, v57
	v_fmac_f32_e32 v28, v98, v58
	v_fmac_f32_e32 v28, v99, v59
	ds_read_b128 v[56:59], v55 offset:20544
	s_waitcnt lgkmcnt(3)
	v_fmac_f32_e32 v27, v96, v60
	v_fmac_f32_e32 v27, v97, v61
	v_fmac_f32_e32 v27, v98, v62
	v_fmac_f32_e32 v27, v99, v63
	ds_read_b128 v[60:63], v55 offset:21568
	s_waitcnt lgkmcnt(3)
	v_fmac_f32_e32 v26, v96, v64
	v_fmac_f32_e32 v26, v97, v65
	v_fmac_f32_e32 v26, v98, v66
	v_fmac_f32_e32 v26, v99, v67
	ds_read_b128 v[64:67], v55 offset:22592
	s_waitcnt lgkmcnt(3)
	v_fmac_f32_e32 v25, v96, v68
	v_fmac_f32_e32 v25, v97, v69
	v_fmac_f32_e32 v25, v98, v70
	v_fmac_f32_e32 v25, v99, v71
	ds_read_b128 v[68:71], v55 offset:23616
	s_waitcnt lgkmcnt(3)
	v_fmac_f32_e32 v24, v96, v56
	v_fmac_f32_e32 v24, v97, v57
	v_fmac_f32_e32 v24, v98, v58
	v_fmac_f32_e32 v24, v99, v59
	ds_read_b128 v[56:59], v55 offset:24640
	s_waitcnt lgkmcnt(3)
	v_fmac_f32_e32 v23, v96, v60
	v_fmac_f32_e32 v23, v97, v61
	v_fmac_f32_e32 v23, v98, v62
	v_fmac_f32_e32 v23, v99, v63
	ds_read_b128 v[60:63], v55 offset:25664
	s_waitcnt lgkmcnt(3)
	v_fmac_f32_e32 v22, v96, v64
	v_fmac_f32_e32 v22, v97, v65
	v_fmac_f32_e32 v22, v98, v66
	v_fmac_f32_e32 v22, v99, v67
	ds_read_b128 v[64:67], v55 offset:26688
	s_waitcnt lgkmcnt(3)
	v_fmac_f32_e32 v21, v96, v68
	v_fmac_f32_e32 v21, v97, v69
	v_fmac_f32_e32 v21, v98, v70
	v_fmac_f32_e32 v21, v99, v71
	ds_read_b128 v[68:71], v55 offset:27712
	s_waitcnt lgkmcnt(3)
	v_fmac_f32_e32 v20, v96, v56
	v_fmac_f32_e32 v20, v97, v57
	v_fmac_f32_e32 v20, v98, v58
	v_fmac_f32_e32 v20, v99, v59
	ds_read_b128 v[56:59], v55 offset:28736
	s_waitcnt lgkmcnt(3)
	v_fmac_f32_e32 v17, v96, v60
	v_fmac_f32_e32 v17, v97, v61
	v_fmac_f32_e32 v17, v98, v62
	v_fmac_f32_e32 v17, v99, v63
	ds_read_b128 v[60:63], v55 offset:29760
	s_waitcnt lgkmcnt(3)
	v_fmac_f32_e32 v16, v96, v64
	v_fmac_f32_e32 v16, v97, v65
	v_fmac_f32_e32 v16, v98, v66
	v_fmac_f32_e32 v16, v99, v67
	ds_read_b128 v[64:67], v55 offset:30784
	s_waitcnt lgkmcnt(3)
	v_fmac_f32_e32 v15, v96, v68
	v_fmac_f32_e32 v15, v97, v69
	v_fmac_f32_e32 v15, v98, v70
	v_fmac_f32_e32 v15, v99, v71
	ds_read_b128 v[68:71], v55 offset:31808
	s_waitcnt lgkmcnt(3)
	v_fmac_f32_e32 v14, v96, v56
	v_fmac_f32_e32 v14, v97, v57
	v_fmac_f32_e32 v14, v98, v58
	v_fmac_f32_e32 v14, v99, v59
	ds_read_b128 v[56:59], v55 offset:32832
	s_waitcnt lgkmcnt(3)
	v_fmac_f32_e32 v13, v96, v60
	v_fmac_f32_e32 v13, v97, v61
	v_fmac_f32_e32 v13, v98, v62
	v_fmac_f32_e32 v13, v99, v63
	ds_read_b128 v[60:63], v55 offset:80
	s_waitcnt lgkmcnt(3)
	v_fmac_f32_e32 v12, v96, v64
	v_fmac_f32_e32 v12, v97, v65
	v_fmac_f32_e32 v12, v98, v66
	v_fmac_f32_e32 v12, v99, v67
	ds_read_b128 v[64:67], v55 offset:1104
	s_waitcnt lgkmcnt(3)
	v_fmac_f32_e32 v11, v96, v68
	v_fmac_f32_e32 v11, v97, v69
	v_fmac_f32_e32 v11, v98, v70
	v_fmac_f32_e32 v11, v99, v71
	ds_read_b128 v[68:71], v55 offset:2128
	s_waitcnt lgkmcnt(3)
	v_fmac_f32_e32 v10, v96, v56
	v_fmac_f32_e32 v10, v97, v57
	v_fmac_f32_e32 v10, v98, v58
	v_fmac_f32_e32 v10, v99, v59
	ds_read_b128 v[56:59], v55 offset:3152
	s_waitcnt lgkmcnt(3)
	v_fmac_f32_e32 v54, v100, v60
	v_fmac_f32_e32 v54, v101, v61
	v_fmac_f32_e32 v54, v102, v62
	v_fmac_f32_e32 v54, v103, v63
	ds_read_b128 v[60:63], v55 offset:4176
	s_waitcnt lgkmcnt(3)
	v_fmac_f32_e32 v43, v100, v64
	v_fmac_f32_e32 v43, v101, v65
	v_fmac_f32_e32 v43, v102, v66
	v_fmac_f32_e32 v43, v103, v67
	ds_read_b128 v[64:67], v55 offset:5200
	s_waitcnt lgkmcnt(3)
	v_fmac_f32_e32 v42, v100, v68
	v_fmac_f32_e32 v42, v101, v69
	v_fmac_f32_e32 v42, v102, v70
	v_fmac_f32_e32 v42, v103, v71
	ds_read_b128 v[68:71], v55 offset:6224
	s_waitcnt lgkmcnt(3)
	v_fmac_f32_e32 v41, v100, v56
	v_fmac_f32_e32 v41, v101, v57
	v_fmac_f32_e32 v41, v102, v58
	v_fmac_f32_e32 v41, v103, v59
	ds_read_b128 v[56:59], v55 offset:7248
	s_waitcnt lgkmcnt(3)
	v_fmac_f32_e32 v40, v100, v60
	v_fmac_f32_e32 v40, v101, v61
	v_fmac_f32_e32 v40, v102, v62
	v_fmac_f32_e32 v40, v103, v63
	ds_read_b128 v[60:63], v55 offset:8272
	s_waitcnt lgkmcnt(3)
	v_fmac_f32_e32 v39, v100, v64
	v_fmac_f32_e32 v39, v101, v65
	v_fmac_f32_e32 v39, v102, v66
	v_fmac_f32_e32 v39, v103, v67
	ds_read_b128 v[64:67], v55 offset:9296
	s_waitcnt lgkmcnt(3)
	v_fmac_f32_e32 v38, v100, v68
	v_fmac_f32_e32 v38, v101, v69
	v_fmac_f32_e32 v38, v102, v70
	v_fmac_f32_e32 v38, v103, v71
	ds_read_b128 v[68:71], v55 offset:10320
	s_waitcnt lgkmcnt(3)
	v_fmac_f32_e32 v37, v100, v56
	v_fmac_f32_e32 v37, v101, v57
	v_fmac_f32_e32 v37, v102, v58
	v_fmac_f32_e32 v37, v103, v59
	ds_read_b128 v[56:59], v55 offset:11344
	s_waitcnt lgkmcnt(3)
	v_fmac_f32_e32 v36, v100, v60
	v_fmac_f32_e32 v36, v101, v61
	v_fmac_f32_e32 v36, v102, v62
	v_fmac_f32_e32 v36, v103, v63
	ds_read_b128 v[60:63], v55 offset:12368
	s_waitcnt lgkmcnt(3)
	v_fmac_f32_e32 v35, v100, v64
	v_fmac_f32_e32 v35, v101, v65
	v_fmac_f32_e32 v35, v102, v66
	v_fmac_f32_e32 v35, v103, v67
	ds_read_b128 v[64:67], v55 offset:13392
	s_waitcnt lgkmcnt(3)
	v_fmac_f32_e32 v34, v100, v68
	v_fmac_f32_e32 v34, v101, v69
	v_fmac_f32_e32 v34, v102, v70
	v_fmac_f32_e32 v34, v103, v71
	ds_read_b128 v[68:71], v55 offset:14416
	s_waitcnt lgkmcnt(3)
	v_fmac_f32_e32 v33, v100, v56
	v_fmac_f32_e32 v33, v101, v57
	v_fmac_f32_e32 v33, v102, v58
	v_fmac_f32_e32 v33, v103, v59
	ds_read_b128 v[56:59], v55 offset:15440
	s_waitcnt lgkmcnt(3)
	v_fmac_f32_e32 v32, v100, v60
	v_fmac_f32_e32 v32, v101, v61
	v_fmac_f32_e32 v32, v102, v62
	v_fmac_f32_e32 v32, v103, v63
	ds_read_b128 v[60:63], v55 offset:16464
	s_waitcnt lgkmcnt(3)
	v_fmac_f32_e32 v31, v100, v64
	v_fmac_f32_e32 v31, v101, v65
	v_fmac_f32_e32 v31, v102, v66
	v_fmac_f32_e32 v31, v103, v67
	ds_read_b128 v[64:67], v55 offset:17488
	s_waitcnt lgkmcnt(3)
	v_fmac_f32_e32 v30, v100, v68
	v_fmac_f32_e32 v30, v101, v69
	v_fmac_f32_e32 v30, v102, v70
	v_fmac_f32_e32 v30, v103, v71
	ds_read_b128 v[68:71], v55 offset:18512
	s_waitcnt lgkmcnt(3)
	v_fmac_f32_e32 v29, v100, v56
	v_fmac_f32_e32 v29, v101, v57
	v_fmac_f32_e32 v29, v102, v58
	v_fmac_f32_e32 v29, v103, v59
	ds_read_b128 v[56:59], v55 offset:19536
	s_waitcnt lgkmcnt(3)
	v_fmac_f32_e32 v28, v100, v60
	v_fmac_f32_e32 v28, v101, v61
	v_fmac_f32_e32 v28, v102, v62
	v_fmac_f32_e32 v28, v103, v63
	ds_read_b128 v[60:63], v55 offset:20560
	s_waitcnt lgkmcnt(3)
	v_fmac_f32_e32 v27, v100, v64
	v_fmac_f32_e32 v27, v101, v65
	v_fmac_f32_e32 v27, v102, v66
	v_fmac_f32_e32 v27, v103, v67
	ds_read_b128 v[64:67], v55 offset:21584
	s_waitcnt lgkmcnt(3)
	v_fmac_f32_e32 v26, v100, v68
	v_fmac_f32_e32 v26, v101, v69
	v_fmac_f32_e32 v26, v102, v70
	v_fmac_f32_e32 v26, v103, v71
	ds_read_b128 v[68:71], v55 offset:22608
	s_waitcnt lgkmcnt(3)
	v_fmac_f32_e32 v25, v100, v56
	v_fmac_f32_e32 v25, v101, v57
	v_fmac_f32_e32 v25, v102, v58
	v_fmac_f32_e32 v25, v103, v59
	ds_read_b128 v[56:59], v55 offset:23632
	s_waitcnt lgkmcnt(3)
	v_fmac_f32_e32 v24, v100, v60
	v_fmac_f32_e32 v24, v101, v61
	v_fmac_f32_e32 v24, v102, v62
	v_fmac_f32_e32 v24, v103, v63
	ds_read_b128 v[60:63], v55 offset:24656
	s_waitcnt lgkmcnt(3)
	v_fmac_f32_e32 v23, v100, v64
	v_fmac_f32_e32 v23, v101, v65
	v_fmac_f32_e32 v23, v102, v66
	v_fmac_f32_e32 v23, v103, v67
	ds_read_b128 v[64:67], v55 offset:25680
	s_waitcnt lgkmcnt(3)
	v_fmac_f32_e32 v22, v100, v68
	v_fmac_f32_e32 v22, v101, v69
	v_fmac_f32_e32 v22, v102, v70
	v_fmac_f32_e32 v22, v103, v71
	ds_read_b128 v[68:71], v55 offset:26704
	s_waitcnt lgkmcnt(3)
	v_fmac_f32_e32 v21, v100, v56
	v_fmac_f32_e32 v21, v101, v57
	v_fmac_f32_e32 v21, v102, v58
	v_fmac_f32_e32 v21, v103, v59
	ds_read_b128 v[56:59], v55 offset:27728
	s_waitcnt lgkmcnt(3)
	v_fmac_f32_e32 v20, v100, v60
	v_fmac_f32_e32 v20, v101, v61
	v_fmac_f32_e32 v20, v102, v62
	v_fmac_f32_e32 v20, v103, v63
	ds_read_b128 v[60:63], v55 offset:28752
	s_waitcnt lgkmcnt(3)
	v_fmac_f32_e32 v17, v100, v64
	v_fmac_f32_e32 v17, v101, v65
	v_fmac_f32_e32 v17, v102, v66
	v_fmac_f32_e32 v17, v103, v67
	ds_read_b128 v[64:67], v55 offset:29776
	s_waitcnt lgkmcnt(3)
	v_fmac_f32_e32 v16, v100, v68
	v_fmac_f32_e32 v16, v101, v69
	v_fmac_f32_e32 v16, v102, v70
	v_fmac_f32_e32 v16, v103, v71
	ds_read_b128 v[68:71], v55 offset:30800
	s_waitcnt lgkmcnt(3)
	v_fmac_f32_e32 v15, v100, v56
	v_fmac_f32_e32 v15, v101, v57
	v_fmac_f32_e32 v15, v102, v58
	v_fmac_f32_e32 v15, v103, v59
	ds_read_b128 v[56:59], v55 offset:31824
	s_waitcnt lgkmcnt(3)
	v_fmac_f32_e32 v14, v100, v60
	v_fmac_f32_e32 v14, v101, v61
	v_fmac_f32_e32 v14, v102, v62
	v_fmac_f32_e32 v14, v103, v63
	ds_read_b128 v[60:63], v55 offset:32848
	s_waitcnt lgkmcnt(3)
	v_fmac_f32_e32 v13, v100, v64
	v_fmac_f32_e32 v13, v101, v65
	v_fmac_f32_e32 v13, v102, v66
	v_fmac_f32_e32 v13, v103, v67
	ds_read_b128 v[64:67], v55 offset:96
	s_waitcnt lgkmcnt(3)
	v_fmac_f32_e32 v12, v100, v68
	v_fmac_f32_e32 v12, v101, v69
	v_fmac_f32_e32 v12, v102, v70
	v_fmac_f32_e32 v12, v103, v71
	ds_read_b128 v[68:71], v55 offset:1120
	s_waitcnt lgkmcnt(3)
	v_fmac_f32_e32 v11, v100, v56
	v_fmac_f32_e32 v11, v101, v57
	v_fmac_f32_e32 v11, v102, v58
	v_fmac_f32_e32 v11, v103, v59
	ds_read_b128 v[56:59], v55 offset:2144
	s_waitcnt lgkmcnt(3)
	v_fmac_f32_e32 v10, v100, v60
	v_fmac_f32_e32 v10, v101, v61
	v_fmac_f32_e32 v10, v102, v62
	v_fmac_f32_e32 v10, v103, v63
	ds_read_b128 v[60:63], v55 offset:3168
	s_waitcnt lgkmcnt(3)
	v_fmac_f32_e32 v54, v104, v64
	v_fmac_f32_e32 v54, v105, v65
	v_fmac_f32_e32 v54, v106, v66
	v_fmac_f32_e32 v54, v107, v67
	ds_read_b128 v[64:67], v55 offset:4192
	s_waitcnt lgkmcnt(3)
	v_fmac_f32_e32 v43, v104, v68
	v_fmac_f32_e32 v43, v105, v69
	v_fmac_f32_e32 v43, v106, v70
	v_fmac_f32_e32 v43, v107, v71
	ds_read_b128 v[68:71], v55 offset:5216
	s_waitcnt lgkmcnt(3)
	v_fmac_f32_e32 v42, v104, v56
	v_fmac_f32_e32 v42, v105, v57
	v_fmac_f32_e32 v42, v106, v58
	v_fmac_f32_e32 v42, v107, v59
	ds_read_b128 v[56:59], v55 offset:6240
	s_waitcnt lgkmcnt(3)
	v_fmac_f32_e32 v41, v104, v60
	v_fmac_f32_e32 v41, v105, v61
	v_fmac_f32_e32 v41, v106, v62
	v_fmac_f32_e32 v41, v107, v63
	ds_read_b128 v[60:63], v55 offset:7264
	s_waitcnt lgkmcnt(3)
	v_fmac_f32_e32 v40, v104, v64
	v_fmac_f32_e32 v40, v105, v65
	v_fmac_f32_e32 v40, v106, v66
	v_fmac_f32_e32 v40, v107, v67
	ds_read_b128 v[64:67], v55 offset:8288
	s_waitcnt lgkmcnt(3)
	v_fmac_f32_e32 v39, v104, v68
	v_fmac_f32_e32 v39, v105, v69
	v_fmac_f32_e32 v39, v106, v70
	v_fmac_f32_e32 v39, v107, v71
	ds_read_b128 v[68:71], v55 offset:9312
	s_waitcnt lgkmcnt(3)
	v_fmac_f32_e32 v38, v104, v56
	v_fmac_f32_e32 v38, v105, v57
	v_fmac_f32_e32 v38, v106, v58
	v_fmac_f32_e32 v38, v107, v59
	ds_read_b128 v[56:59], v55 offset:10336
	s_waitcnt lgkmcnt(3)
	v_fmac_f32_e32 v37, v104, v60
	v_fmac_f32_e32 v37, v105, v61
	v_fmac_f32_e32 v37, v106, v62
	v_fmac_f32_e32 v37, v107, v63
	ds_read_b128 v[60:63], v55 offset:11360
	s_waitcnt lgkmcnt(3)
	v_fmac_f32_e32 v36, v104, v64
	v_fmac_f32_e32 v36, v105, v65
	v_fmac_f32_e32 v36, v106, v66
	v_fmac_f32_e32 v36, v107, v67
	ds_read_b128 v[64:67], v55 offset:12384
	s_waitcnt lgkmcnt(3)
	v_fmac_f32_e32 v35, v104, v68
	v_fmac_f32_e32 v35, v105, v69
	v_fmac_f32_e32 v35, v106, v70
	v_fmac_f32_e32 v35, v107, v71
	ds_read_b128 v[68:71], v55 offset:13408
	s_waitcnt lgkmcnt(3)
	v_fmac_f32_e32 v34, v104, v56
	v_fmac_f32_e32 v34, v105, v57
	v_fmac_f32_e32 v34, v106, v58
	v_fmac_f32_e32 v34, v107, v59
	ds_read_b128 v[56:59], v55 offset:14432
	s_waitcnt lgkmcnt(3)
	v_fmac_f32_e32 v33, v104, v60
	v_fmac_f32_e32 v33, v105, v61
	v_fmac_f32_e32 v33, v106, v62
	v_fmac_f32_e32 v33, v107, v63
	ds_read_b128 v[60:63], v55 offset:15456
	s_waitcnt lgkmcnt(3)
	v_fmac_f32_e32 v32, v104, v64
	v_fmac_f32_e32 v32, v105, v65
	v_fmac_f32_e32 v32, v106, v66
	v_fmac_f32_e32 v32, v107, v67
	ds_read_b128 v[64:67], v55 offset:16480
	s_waitcnt lgkmcnt(3)
	v_fmac_f32_e32 v31, v104, v68
	v_fmac_f32_e32 v31, v105, v69
	v_fmac_f32_e32 v31, v106, v70
	v_fmac_f32_e32 v31, v107, v71
	ds_read_b128 v[68:71], v55 offset:17504
	s_waitcnt lgkmcnt(3)
	v_fmac_f32_e32 v30, v104, v56
	v_fmac_f32_e32 v30, v105, v57
	v_fmac_f32_e32 v30, v106, v58
	v_fmac_f32_e32 v30, v107, v59
	ds_read_b128 v[56:59], v55 offset:18528
	s_waitcnt lgkmcnt(3)
	v_fmac_f32_e32 v29, v104, v60
	v_fmac_f32_e32 v29, v105, v61
	v_fmac_f32_e32 v29, v106, v62
	v_fmac_f32_e32 v29, v107, v63
	ds_read_b128 v[60:63], v55 offset:19552
	s_waitcnt lgkmcnt(3)
	v_fmac_f32_e32 v28, v104, v64
	v_fmac_f32_e32 v28, v105, v65
	v_fmac_f32_e32 v28, v106, v66
	v_fmac_f32_e32 v28, v107, v67
	ds_read_b128 v[64:67], v55 offset:20576
	s_waitcnt lgkmcnt(3)
	v_fmac_f32_e32 v27, v104, v68
	v_fmac_f32_e32 v27, v105, v69
	v_fmac_f32_e32 v27, v106, v70
	v_fmac_f32_e32 v27, v107, v71
	ds_read_b128 v[68:71], v55 offset:21600
	s_waitcnt lgkmcnt(3)
	v_fmac_f32_e32 v26, v104, v56
	v_fmac_f32_e32 v26, v105, v57
	v_fmac_f32_e32 v26, v106, v58
	v_fmac_f32_e32 v26, v107, v59
	ds_read_b128 v[56:59], v55 offset:22624
	s_waitcnt lgkmcnt(3)
	v_fmac_f32_e32 v25, v104, v60
	v_fmac_f32_e32 v25, v105, v61
	v_fmac_f32_e32 v25, v106, v62
	v_fmac_f32_e32 v25, v107, v63
	ds_read_b128 v[60:63], v55 offset:23648
	s_waitcnt lgkmcnt(3)
	v_fmac_f32_e32 v24, v104, v64
	v_fmac_f32_e32 v24, v105, v65
	v_fmac_f32_e32 v24, v106, v66
	v_fmac_f32_e32 v24, v107, v67
	ds_read_b128 v[64:67], v55 offset:24672
	s_waitcnt lgkmcnt(3)
	v_fmac_f32_e32 v23, v104, v68
	v_fmac_f32_e32 v23, v105, v69
	v_fmac_f32_e32 v23, v106, v70
	v_fmac_f32_e32 v23, v107, v71
	ds_read_b128 v[68:71], v55 offset:25696
	s_waitcnt lgkmcnt(3)
	v_fmac_f32_e32 v22, v104, v56
	v_fmac_f32_e32 v22, v105, v57
	v_fmac_f32_e32 v22, v106, v58
	v_fmac_f32_e32 v22, v107, v59
	ds_read_b128 v[56:59], v55 offset:26720
	s_waitcnt lgkmcnt(3)
	v_fmac_f32_e32 v21, v104, v60
	v_fmac_f32_e32 v21, v105, v61
	v_fmac_f32_e32 v21, v106, v62
	v_fmac_f32_e32 v21, v107, v63
	ds_read_b128 v[60:63], v55 offset:27744
	s_waitcnt lgkmcnt(3)
	v_fmac_f32_e32 v20, v104, v64
	v_fmac_f32_e32 v20, v105, v65
	v_fmac_f32_e32 v20, v106, v66
	v_fmac_f32_e32 v20, v107, v67
	ds_read_b128 v[64:67], v55 offset:28768
	s_waitcnt lgkmcnt(3)
	v_fmac_f32_e32 v17, v104, v68
	v_fmac_f32_e32 v17, v105, v69
	v_fmac_f32_e32 v17, v106, v70
	v_fmac_f32_e32 v17, v107, v71
	ds_read_b128 v[68:71], v55 offset:29792
	s_waitcnt lgkmcnt(3)
	v_fmac_f32_e32 v16, v104, v56
	v_fmac_f32_e32 v16, v105, v57
	v_fmac_f32_e32 v16, v106, v58
	v_fmac_f32_e32 v16, v107, v59
	ds_read_b128 v[56:59], v55 offset:30816
	s_waitcnt lgkmcnt(3)
	v_fmac_f32_e32 v15, v104, v60
	v_fmac_f32_e32 v15, v105, v61
	v_fmac_f32_e32 v15, v106, v62
	v_fmac_f32_e32 v15, v107, v63
	ds_read_b128 v[60:63], v55 offset:31840
	s_waitcnt lgkmcnt(3)
	v_fmac_f32_e32 v14, v104, v64
	v_fmac_f32_e32 v14, v105, v65
	v_fmac_f32_e32 v14, v106, v66
	v_fmac_f32_e32 v14, v107, v67
	ds_read_b128 v[64:67], v55 offset:32864
	s_waitcnt lgkmcnt(3)
	v_fmac_f32_e32 v13, v104, v68
	v_fmac_f32_e32 v13, v105, v69
	v_fmac_f32_e32 v13, v106, v70
	v_fmac_f32_e32 v13, v107, v71
	ds_read_b128 v[68:71], v55 offset:112
	s_waitcnt lgkmcnt(3)
	v_fmac_f32_e32 v12, v104, v56
	v_fmac_f32_e32 v12, v105, v57
	v_fmac_f32_e32 v12, v106, v58
	v_fmac_f32_e32 v12, v107, v59
	ds_read_b128 v[56:59], v55 offset:1136
	s_waitcnt lgkmcnt(3)
	v_fmac_f32_e32 v11, v104, v60
	v_fmac_f32_e32 v11, v105, v61
	v_fmac_f32_e32 v11, v106, v62
	v_fmac_f32_e32 v11, v107, v63
	ds_read_b128 v[60:63], v55 offset:2160
	s_waitcnt lgkmcnt(3)
	v_fmac_f32_e32 v10, v104, v64
	v_fmac_f32_e32 v10, v105, v65
	v_fmac_f32_e32 v10, v106, v66
	v_fmac_f32_e32 v10, v107, v67
	ds_read_b128 v[64:67], v55 offset:3184
	s_waitcnt lgkmcnt(3)
	v_fmac_f32_e32 v54, v108, v68
	v_fmac_f32_e32 v54, v109, v69
	v_fmac_f32_e32 v54, v110, v70
	v_fmac_f32_e32 v54, v111, v71
	ds_read_b128 v[68:71], v55 offset:4208
	s_waitcnt lgkmcnt(3)
	v_fmac_f32_e32 v43, v108, v56
	v_fmac_f32_e32 v43, v109, v57
	v_fmac_f32_e32 v43, v110, v58
	v_fmac_f32_e32 v43, v111, v59
	ds_read_b128 v[56:59], v55 offset:5232
	s_waitcnt lgkmcnt(3)
	v_fmac_f32_e32 v42, v108, v60
	v_fmac_f32_e32 v42, v109, v61
	v_fmac_f32_e32 v42, v110, v62
	v_fmac_f32_e32 v42, v111, v63
	ds_read_b128 v[60:63], v55 offset:6256
	s_waitcnt lgkmcnt(3)
	v_fmac_f32_e32 v41, v108, v64
	v_fmac_f32_e32 v41, v109, v65
	v_fmac_f32_e32 v41, v110, v66
	v_fmac_f32_e32 v41, v111, v67
	ds_read_b128 v[64:67], v55 offset:7280
	s_waitcnt lgkmcnt(3)
	v_fmac_f32_e32 v40, v108, v68
	v_fmac_f32_e32 v40, v109, v69
	v_fmac_f32_e32 v40, v110, v70
	v_fmac_f32_e32 v40, v111, v71
	ds_read_b128 v[68:71], v55 offset:8304
	s_waitcnt lgkmcnt(3)
	v_fmac_f32_e32 v39, v108, v56
	v_fmac_f32_e32 v39, v109, v57
	v_fmac_f32_e32 v39, v110, v58
	v_fmac_f32_e32 v39, v111, v59
	ds_read_b128 v[56:59], v55 offset:9328
	s_waitcnt lgkmcnt(3)
	v_fmac_f32_e32 v38, v108, v60
	v_fmac_f32_e32 v38, v109, v61
	v_fmac_f32_e32 v38, v110, v62
	v_fmac_f32_e32 v38, v111, v63
	ds_read_b128 v[60:63], v55 offset:10352
	s_waitcnt lgkmcnt(3)
	v_fmac_f32_e32 v37, v108, v64
	v_fmac_f32_e32 v37, v109, v65
	v_fmac_f32_e32 v37, v110, v66
	v_fmac_f32_e32 v37, v111, v67
	ds_read_b128 v[64:67], v55 offset:11376
	s_waitcnt lgkmcnt(3)
	v_fmac_f32_e32 v36, v108, v68
	v_fmac_f32_e32 v36, v109, v69
	v_fmac_f32_e32 v36, v110, v70
	v_fmac_f32_e32 v36, v111, v71
	ds_read_b128 v[68:71], v55 offset:12400
	s_waitcnt lgkmcnt(3)
	v_fmac_f32_e32 v35, v108, v56
	v_fmac_f32_e32 v35, v109, v57
	v_fmac_f32_e32 v35, v110, v58
	v_fmac_f32_e32 v35, v111, v59
	ds_read_b128 v[56:59], v55 offset:13424
	s_waitcnt lgkmcnt(3)
	v_fmac_f32_e32 v34, v108, v60
	v_fmac_f32_e32 v34, v109, v61
	v_fmac_f32_e32 v34, v110, v62
	v_fmac_f32_e32 v34, v111, v63
	ds_read_b128 v[60:63], v55 offset:14448
	s_waitcnt lgkmcnt(3)
	v_fmac_f32_e32 v33, v108, v64
	v_fmac_f32_e32 v33, v109, v65
	v_fmac_f32_e32 v33, v110, v66
	v_fmac_f32_e32 v33, v111, v67
	ds_read_b128 v[64:67], v55 offset:15472
	s_waitcnt lgkmcnt(3)
	v_fmac_f32_e32 v32, v108, v68
	v_fmac_f32_e32 v32, v109, v69
	v_fmac_f32_e32 v32, v110, v70
	v_fmac_f32_e32 v32, v111, v71
	ds_read_b128 v[68:71], v55 offset:16496
	s_waitcnt lgkmcnt(3)
	v_fmac_f32_e32 v31, v108, v56
	v_fmac_f32_e32 v31, v109, v57
	v_fmac_f32_e32 v31, v110, v58
	v_fmac_f32_e32 v31, v111, v59
	ds_read_b128 v[56:59], v55 offset:17520
	s_waitcnt lgkmcnt(3)
	v_fmac_f32_e32 v30, v108, v60
	v_fmac_f32_e32 v30, v109, v61
	v_fmac_f32_e32 v30, v110, v62
	v_fmac_f32_e32 v30, v111, v63
	ds_read_b128 v[60:63], v55 offset:18544
	s_waitcnt lgkmcnt(3)
	v_fmac_f32_e32 v29, v108, v64
	v_fmac_f32_e32 v29, v109, v65
	v_fmac_f32_e32 v29, v110, v66
	v_fmac_f32_e32 v29, v111, v67
	ds_read_b128 v[64:67], v55 offset:19568
	s_waitcnt lgkmcnt(3)
	v_fmac_f32_e32 v28, v108, v68
	v_fmac_f32_e32 v28, v109, v69
	v_fmac_f32_e32 v28, v110, v70
	v_fmac_f32_e32 v28, v111, v71
	ds_read_b128 v[68:71], v55 offset:20592
	s_waitcnt lgkmcnt(3)
	v_fmac_f32_e32 v27, v108, v56
	v_fmac_f32_e32 v27, v109, v57
	v_fmac_f32_e32 v27, v110, v58
	v_fmac_f32_e32 v27, v111, v59
	ds_read_b128 v[56:59], v55 offset:21616
	s_waitcnt lgkmcnt(3)
	v_fmac_f32_e32 v26, v108, v60
	v_fmac_f32_e32 v26, v109, v61
	v_fmac_f32_e32 v26, v110, v62
	v_fmac_f32_e32 v26, v111, v63
	ds_read_b128 v[60:63], v55 offset:22640
	s_waitcnt lgkmcnt(3)
	v_fmac_f32_e32 v25, v108, v64
	v_fmac_f32_e32 v25, v109, v65
	v_fmac_f32_e32 v25, v110, v66
	v_fmac_f32_e32 v25, v111, v67
	ds_read_b128 v[64:67], v55 offset:23664
	s_waitcnt lgkmcnt(3)
	v_fmac_f32_e32 v24, v108, v68
	v_fmac_f32_e32 v24, v109, v69
	v_fmac_f32_e32 v24, v110, v70
	v_fmac_f32_e32 v24, v111, v71
	ds_read_b128 v[68:71], v55 offset:24688
	s_waitcnt lgkmcnt(3)
	v_fmac_f32_e32 v23, v108, v56
	v_fmac_f32_e32 v23, v109, v57
	v_fmac_f32_e32 v23, v110, v58
	v_fmac_f32_e32 v23, v111, v59
	ds_read_b128 v[56:59], v55 offset:25712
	s_waitcnt lgkmcnt(3)
	v_fmac_f32_e32 v22, v108, v60
	v_fmac_f32_e32 v22, v109, v61
	v_fmac_f32_e32 v22, v110, v62
	v_fmac_f32_e32 v22, v111, v63
	ds_read_b128 v[60:63], v55 offset:26736
	s_waitcnt lgkmcnt(3)
	v_fmac_f32_e32 v21, v108, v64
	v_fmac_f32_e32 v21, v109, v65
	v_fmac_f32_e32 v21, v110, v66
	v_fmac_f32_e32 v21, v111, v67
	ds_read_b128 v[64:67], v55 offset:27760
	s_waitcnt lgkmcnt(3)
	v_fmac_f32_e32 v20, v108, v68
	v_fmac_f32_e32 v20, v109, v69
	v_fmac_f32_e32 v20, v110, v70
	v_fmac_f32_e32 v20, v111, v71
	ds_read_b128 v[68:71], v55 offset:28784
	s_waitcnt lgkmcnt(3)
	v_fmac_f32_e32 v17, v108, v56
	v_fmac_f32_e32 v17, v109, v57
	v_fmac_f32_e32 v17, v110, v58
	v_fmac_f32_e32 v17, v111, v59
	ds_read_b128 v[56:59], v55 offset:29808
	s_waitcnt lgkmcnt(3)
	v_fmac_f32_e32 v16, v108, v60
	v_fmac_f32_e32 v16, v109, v61
	v_fmac_f32_e32 v16, v110, v62
	v_fmac_f32_e32 v16, v111, v63
	ds_read_b128 v[60:63], v55 offset:30832
	s_waitcnt lgkmcnt(3)
	v_fmac_f32_e32 v15, v108, v64
	v_fmac_f32_e32 v15, v109, v65
	v_fmac_f32_e32 v15, v110, v66
	v_fmac_f32_e32 v15, v111, v67
	ds_read_b128 v[64:67], v55 offset:31856
	s_waitcnt lgkmcnt(3)
	v_fmac_f32_e32 v14, v108, v68
	v_fmac_f32_e32 v14, v109, v69
	v_fmac_f32_e32 v14, v110, v70
	v_fmac_f32_e32 v14, v111, v71
	ds_read_b128 v[68:71], v55 offset:32880
	s_waitcnt lgkmcnt(3)
	v_fmac_f32_e32 v13, v108, v56
	v_fmac_f32_e32 v13, v109, v57
	v_fmac_f32_e32 v13, v110, v58
	v_fmac_f32_e32 v13, v111, v59
	ds_read_b128 v[56:59], v55 offset:128
	s_waitcnt lgkmcnt(3)
	v_fmac_f32_e32 v12, v108, v60
	v_fmac_f32_e32 v12, v109, v61
	v_fmac_f32_e32 v12, v110, v62
	v_fmac_f32_e32 v12, v111, v63
	ds_read_b128 v[60:63], v55 offset:1152
	s_waitcnt lgkmcnt(3)
	v_fmac_f32_e32 v11, v108, v64
	v_fmac_f32_e32 v11, v109, v65
	v_fmac_f32_e32 v11, v110, v66
	v_fmac_f32_e32 v11, v111, v67
	ds_read_b128 v[64:67], v55 offset:2176
	s_waitcnt lgkmcnt(3)
	v_fmac_f32_e32 v10, v108, v68
	v_fmac_f32_e32 v10, v109, v69
	v_fmac_f32_e32 v10, v110, v70
	v_fmac_f32_e32 v10, v111, v71
	ds_read_b128 v[68:71], v55 offset:3200
	s_waitcnt lgkmcnt(3)
	v_fmac_f32_e32 v54, v112, v56
	v_fmac_f32_e32 v54, v113, v57
	v_fmac_f32_e32 v54, v114, v58
	v_fmac_f32_e32 v54, v115, v59
	ds_read_b128 v[56:59], v55 offset:4224
	s_waitcnt lgkmcnt(3)
	v_fmac_f32_e32 v43, v112, v60
	v_fmac_f32_e32 v43, v113, v61
	v_fmac_f32_e32 v43, v114, v62
	v_fmac_f32_e32 v43, v115, v63
	ds_read_b128 v[60:63], v55 offset:5248
	s_waitcnt lgkmcnt(3)
	v_fmac_f32_e32 v42, v112, v64
	v_fmac_f32_e32 v42, v113, v65
	v_fmac_f32_e32 v42, v114, v66
	v_fmac_f32_e32 v42, v115, v67
	ds_read_b128 v[64:67], v55 offset:6272
	s_waitcnt lgkmcnt(3)
	v_fmac_f32_e32 v41, v112, v68
	v_fmac_f32_e32 v41, v113, v69
	v_fmac_f32_e32 v41, v114, v70
	v_fmac_f32_e32 v41, v115, v71
	ds_read_b128 v[68:71], v55 offset:7296
	s_waitcnt lgkmcnt(3)
	v_fmac_f32_e32 v40, v112, v56
	v_fmac_f32_e32 v40, v113, v57
	v_fmac_f32_e32 v40, v114, v58
	v_fmac_f32_e32 v40, v115, v59
	ds_read_b128 v[56:59], v55 offset:8320
	s_waitcnt lgkmcnt(3)
	v_fmac_f32_e32 v39, v112, v60
	v_fmac_f32_e32 v39, v113, v61
	v_fmac_f32_e32 v39, v114, v62
	v_fmac_f32_e32 v39, v115, v63
	ds_read_b128 v[60:63], v55 offset:9344
	s_waitcnt lgkmcnt(3)
	v_fmac_f32_e32 v38, v112, v64
	v_fmac_f32_e32 v38, v113, v65
	v_fmac_f32_e32 v38, v114, v66
	v_fmac_f32_e32 v38, v115, v67
	ds_read_b128 v[64:67], v55 offset:10368
	s_waitcnt lgkmcnt(3)
	v_fmac_f32_e32 v37, v112, v68
	v_fmac_f32_e32 v37, v113, v69
	v_fmac_f32_e32 v37, v114, v70
	v_fmac_f32_e32 v37, v115, v71
	ds_read_b128 v[68:71], v55 offset:11392
	s_waitcnt lgkmcnt(3)
	v_fmac_f32_e32 v36, v112, v56
	v_fmac_f32_e32 v36, v113, v57
	v_fmac_f32_e32 v36, v114, v58
	v_fmac_f32_e32 v36, v115, v59
	ds_read_b128 v[56:59], v55 offset:12416
	s_waitcnt lgkmcnt(3)
	v_fmac_f32_e32 v35, v112, v60
	v_fmac_f32_e32 v35, v113, v61
	v_fmac_f32_e32 v35, v114, v62
	v_fmac_f32_e32 v35, v115, v63
	ds_read_b128 v[60:63], v55 offset:13440
	s_waitcnt lgkmcnt(3)
	v_fmac_f32_e32 v34, v112, v64
	v_fmac_f32_e32 v34, v113, v65
	v_fmac_f32_e32 v34, v114, v66
	v_fmac_f32_e32 v34, v115, v67
	ds_read_b128 v[64:67], v55 offset:14464
	s_waitcnt lgkmcnt(3)
	v_fmac_f32_e32 v33, v112, v68
	v_fmac_f32_e32 v33, v113, v69
	v_fmac_f32_e32 v33, v114, v70
	v_fmac_f32_e32 v33, v115, v71
	ds_read_b128 v[68:71], v55 offset:15488
	s_waitcnt lgkmcnt(3)
	v_fmac_f32_e32 v32, v112, v56
	v_fmac_f32_e32 v32, v113, v57
	v_fmac_f32_e32 v32, v114, v58
	v_fmac_f32_e32 v32, v115, v59
	ds_read_b128 v[56:59], v55 offset:16512
	s_waitcnt lgkmcnt(3)
	v_fmac_f32_e32 v31, v112, v60
	v_fmac_f32_e32 v31, v113, v61
	v_fmac_f32_e32 v31, v114, v62
	v_fmac_f32_e32 v31, v115, v63
	ds_read_b128 v[60:63], v55 offset:17536
	s_waitcnt lgkmcnt(3)
	v_fmac_f32_e32 v30, v112, v64
	v_fmac_f32_e32 v30, v113, v65
	v_fmac_f32_e32 v30, v114, v66
	v_fmac_f32_e32 v30, v115, v67
	ds_read_b128 v[64:67], v55 offset:18560
	s_waitcnt lgkmcnt(3)
	v_fmac_f32_e32 v29, v112, v68
	v_fmac_f32_e32 v29, v113, v69
	v_fmac_f32_e32 v29, v114, v70
	v_fmac_f32_e32 v29, v115, v71
	ds_read_b128 v[68:71], v55 offset:19584
	s_waitcnt lgkmcnt(3)
	v_fmac_f32_e32 v28, v112, v56
	v_fmac_f32_e32 v28, v113, v57
	v_fmac_f32_e32 v28, v114, v58
	v_fmac_f32_e32 v28, v115, v59
	ds_read_b128 v[56:59], v55 offset:20608
	s_waitcnt lgkmcnt(3)
	v_fmac_f32_e32 v27, v112, v60
	v_fmac_f32_e32 v27, v113, v61
	v_fmac_f32_e32 v27, v114, v62
	v_fmac_f32_e32 v27, v115, v63
	ds_read_b128 v[60:63], v55 offset:21632
	s_waitcnt lgkmcnt(3)
	v_fmac_f32_e32 v26, v112, v64
	v_fmac_f32_e32 v26, v113, v65
	v_fmac_f32_e32 v26, v114, v66
	v_fmac_f32_e32 v26, v115, v67
	ds_read_b128 v[64:67], v55 offset:22656
	s_waitcnt lgkmcnt(3)
	v_fmac_f32_e32 v25, v112, v68
	v_fmac_f32_e32 v25, v113, v69
	v_fmac_f32_e32 v25, v114, v70
	v_fmac_f32_e32 v25, v115, v71
	ds_read_b128 v[68:71], v55 offset:23680
	s_waitcnt lgkmcnt(3)
	v_fmac_f32_e32 v24, v112, v56
	v_fmac_f32_e32 v24, v113, v57
	v_fmac_f32_e32 v24, v114, v58
	v_fmac_f32_e32 v24, v115, v59
	ds_read_b128 v[56:59], v55 offset:24704
	s_waitcnt lgkmcnt(3)
	v_fmac_f32_e32 v23, v112, v60
	v_fmac_f32_e32 v23, v113, v61
	v_fmac_f32_e32 v23, v114, v62
	v_fmac_f32_e32 v23, v115, v63
	ds_read_b128 v[60:63], v55 offset:25728
	s_waitcnt lgkmcnt(3)
	v_fmac_f32_e32 v22, v112, v64
	v_fmac_f32_e32 v22, v113, v65
	v_fmac_f32_e32 v22, v114, v66
	v_fmac_f32_e32 v22, v115, v67
	ds_read_b128 v[64:67], v55 offset:26752
	s_waitcnt lgkmcnt(3)
	v_fmac_f32_e32 v21, v112, v68
	v_fmac_f32_e32 v21, v113, v69
	v_fmac_f32_e32 v21, v114, v70
	v_fmac_f32_e32 v21, v115, v71
	ds_read_b128 v[68:71], v55 offset:27776
	s_waitcnt lgkmcnt(3)
	v_fmac_f32_e32 v20, v112, v56
	v_fmac_f32_e32 v20, v113, v57
	v_fmac_f32_e32 v20, v114, v58
	v_fmac_f32_e32 v20, v115, v59
	ds_read_b128 v[56:59], v55 offset:28800
	s_waitcnt lgkmcnt(3)
	v_fmac_f32_e32 v17, v112, v60
	v_fmac_f32_e32 v17, v113, v61
	v_fmac_f32_e32 v17, v114, v62
	v_fmac_f32_e32 v17, v115, v63
	ds_read_b128 v[60:63], v55 offset:29824
	s_waitcnt lgkmcnt(3)
	v_fmac_f32_e32 v16, v112, v64
	v_fmac_f32_e32 v16, v113, v65
	v_fmac_f32_e32 v16, v114, v66
	v_fmac_f32_e32 v16, v115, v67
	ds_read_b128 v[64:67], v55 offset:30848
	s_waitcnt lgkmcnt(3)
	v_fmac_f32_e32 v15, v112, v68
	v_fmac_f32_e32 v15, v113, v69
	v_fmac_f32_e32 v15, v114, v70
	v_fmac_f32_e32 v15, v115, v71
	ds_read_b128 v[68:71], v55 offset:31872
	s_waitcnt lgkmcnt(3)
	v_fmac_f32_e32 v14, v112, v56
	v_fmac_f32_e32 v14, v113, v57
	v_fmac_f32_e32 v14, v114, v58
	v_fmac_f32_e32 v14, v115, v59
	ds_read_b128 v[56:59], v55 offset:32896
	s_waitcnt lgkmcnt(3)
	v_fmac_f32_e32 v13, v112, v60
	v_fmac_f32_e32 v13, v113, v61
	v_fmac_f32_e32 v13, v114, v62
	v_fmac_f32_e32 v13, v115, v63
	ds_read_b128 v[60:63], v55 offset:144
	s_waitcnt lgkmcnt(3)
	v_fmac_f32_e32 v12, v112, v64
	v_fmac_f32_e32 v12, v113, v65
	v_fmac_f32_e32 v12, v114, v66
	v_fmac_f32_e32 v12, v115, v67
	ds_read_b128 v[64:67], v55 offset:1168
	s_waitcnt lgkmcnt(3)
	v_fmac_f32_e32 v11, v112, v68
	v_fmac_f32_e32 v11, v113, v69
	v_fmac_f32_e32 v11, v114, v70
	v_fmac_f32_e32 v11, v115, v71
	ds_read_b128 v[68:71], v55 offset:2192
	s_waitcnt lgkmcnt(3)
	v_fmac_f32_e32 v10, v112, v56
	v_fmac_f32_e32 v10, v113, v57
	v_fmac_f32_e32 v10, v114, v58
	v_fmac_f32_e32 v10, v115, v59
	ds_read_b128 v[56:59], v55 offset:3216
	s_waitcnt lgkmcnt(3)
	v_fmac_f32_e32 v54, v116, v60
	v_fmac_f32_e32 v54, v117, v61
	v_fmac_f32_e32 v54, v118, v62
	v_fmac_f32_e32 v54, v119, v63
	ds_read_b128 v[60:63], v55 offset:4240
	s_waitcnt lgkmcnt(3)
	v_fmac_f32_e32 v43, v116, v64
	v_fmac_f32_e32 v43, v117, v65
	v_fmac_f32_e32 v43, v118, v66
	v_fmac_f32_e32 v43, v119, v67
	ds_read_b128 v[64:67], v55 offset:5264
	s_waitcnt lgkmcnt(3)
	v_fmac_f32_e32 v42, v116, v68
	v_fmac_f32_e32 v42, v117, v69
	v_fmac_f32_e32 v42, v118, v70
	v_fmac_f32_e32 v42, v119, v71
	ds_read_b128 v[68:71], v55 offset:6288
	s_waitcnt lgkmcnt(3)
	v_fmac_f32_e32 v41, v116, v56
	v_fmac_f32_e32 v41, v117, v57
	v_fmac_f32_e32 v41, v118, v58
	v_fmac_f32_e32 v41, v119, v59
	ds_read_b128 v[56:59], v55 offset:7312
	s_waitcnt lgkmcnt(3)
	v_fmac_f32_e32 v40, v116, v60
	v_fmac_f32_e32 v40, v117, v61
	v_fmac_f32_e32 v40, v118, v62
	v_fmac_f32_e32 v40, v119, v63
	ds_read_b128 v[60:63], v55 offset:8336
	s_waitcnt lgkmcnt(3)
	v_fmac_f32_e32 v39, v116, v64
	v_fmac_f32_e32 v39, v117, v65
	v_fmac_f32_e32 v39, v118, v66
	v_fmac_f32_e32 v39, v119, v67
	ds_read_b128 v[64:67], v55 offset:9360
	s_waitcnt lgkmcnt(3)
	v_fmac_f32_e32 v38, v116, v68
	v_fmac_f32_e32 v38, v117, v69
	v_fmac_f32_e32 v38, v118, v70
	v_fmac_f32_e32 v38, v119, v71
	ds_read_b128 v[68:71], v55 offset:10384
	s_waitcnt lgkmcnt(3)
	v_fmac_f32_e32 v37, v116, v56
	v_fmac_f32_e32 v37, v117, v57
	v_fmac_f32_e32 v37, v118, v58
	v_fmac_f32_e32 v37, v119, v59
	ds_read_b128 v[56:59], v55 offset:11408
	s_waitcnt lgkmcnt(3)
	v_fmac_f32_e32 v36, v116, v60
	v_fmac_f32_e32 v36, v117, v61
	v_fmac_f32_e32 v36, v118, v62
	v_fmac_f32_e32 v36, v119, v63
	ds_read_b128 v[60:63], v55 offset:12432
	s_waitcnt lgkmcnt(3)
	v_fmac_f32_e32 v35, v116, v64
	v_fmac_f32_e32 v35, v117, v65
	v_fmac_f32_e32 v35, v118, v66
	v_fmac_f32_e32 v35, v119, v67
	ds_read_b128 v[64:67], v55 offset:13456
	s_waitcnt lgkmcnt(3)
	v_fmac_f32_e32 v34, v116, v68
	v_fmac_f32_e32 v34, v117, v69
	v_fmac_f32_e32 v34, v118, v70
	v_fmac_f32_e32 v34, v119, v71
	ds_read_b128 v[68:71], v55 offset:14480
	s_waitcnt lgkmcnt(3)
	v_fmac_f32_e32 v33, v116, v56
	v_fmac_f32_e32 v33, v117, v57
	v_fmac_f32_e32 v33, v118, v58
	v_fmac_f32_e32 v33, v119, v59
	ds_read_b128 v[56:59], v55 offset:15504
	s_waitcnt lgkmcnt(3)
	v_fmac_f32_e32 v32, v116, v60
	v_fmac_f32_e32 v32, v117, v61
	v_fmac_f32_e32 v32, v118, v62
	v_fmac_f32_e32 v32, v119, v63
	ds_read_b128 v[60:63], v55 offset:16528
	s_waitcnt lgkmcnt(3)
	v_fmac_f32_e32 v31, v116, v64
	v_fmac_f32_e32 v31, v117, v65
	v_fmac_f32_e32 v31, v118, v66
	v_fmac_f32_e32 v31, v119, v67
	ds_read_b128 v[64:67], v55 offset:17552
	s_waitcnt lgkmcnt(3)
	v_fmac_f32_e32 v30, v116, v68
	v_fmac_f32_e32 v30, v117, v69
	v_fmac_f32_e32 v30, v118, v70
	v_fmac_f32_e32 v30, v119, v71
	ds_read_b128 v[68:71], v55 offset:18576
	s_waitcnt lgkmcnt(3)
	v_fmac_f32_e32 v29, v116, v56
	v_fmac_f32_e32 v29, v117, v57
	v_fmac_f32_e32 v29, v118, v58
	v_fmac_f32_e32 v29, v119, v59
	ds_read_b128 v[56:59], v55 offset:19600
	s_waitcnt lgkmcnt(3)
	v_fmac_f32_e32 v28, v116, v60
	v_fmac_f32_e32 v28, v117, v61
	v_fmac_f32_e32 v28, v118, v62
	v_fmac_f32_e32 v28, v119, v63
	ds_read_b128 v[60:63], v55 offset:20624
	s_waitcnt lgkmcnt(3)
	v_fmac_f32_e32 v27, v116, v64
	v_fmac_f32_e32 v27, v117, v65
	v_fmac_f32_e32 v27, v118, v66
	v_fmac_f32_e32 v27, v119, v67
	ds_read_b128 v[64:67], v55 offset:21648
	s_waitcnt lgkmcnt(3)
	v_fmac_f32_e32 v26, v116, v68
	v_fmac_f32_e32 v26, v117, v69
	v_fmac_f32_e32 v26, v118, v70
	v_fmac_f32_e32 v26, v119, v71
	ds_read_b128 v[68:71], v55 offset:22672
	s_waitcnt lgkmcnt(3)
	v_fmac_f32_e32 v25, v116, v56
	v_fmac_f32_e32 v25, v117, v57
	v_fmac_f32_e32 v25, v118, v58
	v_fmac_f32_e32 v25, v119, v59
	ds_read_b128 v[56:59], v55 offset:23696
	s_waitcnt lgkmcnt(3)
	v_fmac_f32_e32 v24, v116, v60
	v_fmac_f32_e32 v24, v117, v61
	v_fmac_f32_e32 v24, v118, v62
	v_fmac_f32_e32 v24, v119, v63
	ds_read_b128 v[60:63], v55 offset:24720
	s_waitcnt lgkmcnt(3)
	v_fmac_f32_e32 v23, v116, v64
	v_fmac_f32_e32 v23, v117, v65
	v_fmac_f32_e32 v23, v118, v66
	v_fmac_f32_e32 v23, v119, v67
	ds_read_b128 v[64:67], v55 offset:25744
	s_waitcnt lgkmcnt(3)
	v_fmac_f32_e32 v22, v116, v68
	v_fmac_f32_e32 v22, v117, v69
	v_fmac_f32_e32 v22, v118, v70
	v_fmac_f32_e32 v22, v119, v71
	ds_read_b128 v[68:71], v55 offset:26768
	s_waitcnt lgkmcnt(3)
	v_fmac_f32_e32 v21, v116, v56
	v_fmac_f32_e32 v21, v117, v57
	v_fmac_f32_e32 v21, v118, v58
	v_fmac_f32_e32 v21, v119, v59
	ds_read_b128 v[56:59], v55 offset:27792
	s_waitcnt lgkmcnt(3)
	v_fmac_f32_e32 v20, v116, v60
	v_fmac_f32_e32 v20, v117, v61
	v_fmac_f32_e32 v20, v118, v62
	v_fmac_f32_e32 v20, v119, v63
	ds_read_b128 v[60:63], v55 offset:28816
	s_waitcnt lgkmcnt(3)
	v_fmac_f32_e32 v17, v116, v64
	v_fmac_f32_e32 v17, v117, v65
	v_fmac_f32_e32 v17, v118, v66
	v_fmac_f32_e32 v17, v119, v67
	ds_read_b128 v[64:67], v55 offset:29840
	s_waitcnt lgkmcnt(3)
	v_fmac_f32_e32 v16, v116, v68
	v_fmac_f32_e32 v16, v117, v69
	v_fmac_f32_e32 v16, v118, v70
	v_fmac_f32_e32 v16, v119, v71
	ds_read_b128 v[68:71], v55 offset:30864
	s_waitcnt lgkmcnt(3)
	v_fmac_f32_e32 v15, v116, v56
	v_fmac_f32_e32 v15, v117, v57
	v_fmac_f32_e32 v15, v118, v58
	v_fmac_f32_e32 v15, v119, v59
	ds_read_b128 v[56:59], v55 offset:31888
	s_waitcnt lgkmcnt(3)
	v_fmac_f32_e32 v14, v116, v60
	v_fmac_f32_e32 v14, v117, v61
	v_fmac_f32_e32 v14, v118, v62
	v_fmac_f32_e32 v14, v119, v63
	ds_read_b128 v[60:63], v55 offset:32912
	s_waitcnt lgkmcnt(3)
	v_fmac_f32_e32 v13, v116, v64
	v_fmac_f32_e32 v13, v117, v65
	v_fmac_f32_e32 v13, v118, v66
	v_fmac_f32_e32 v13, v119, v67
	ds_read_b128 v[64:67], v55 offset:160
	s_waitcnt lgkmcnt(3)
	v_fmac_f32_e32 v12, v116, v68
	v_fmac_f32_e32 v12, v117, v69
	v_fmac_f32_e32 v12, v118, v70
	v_fmac_f32_e32 v12, v119, v71
	ds_read_b128 v[68:71], v55 offset:1184
	s_waitcnt lgkmcnt(3)
	v_fmac_f32_e32 v11, v116, v56
	v_fmac_f32_e32 v11, v117, v57
	v_fmac_f32_e32 v11, v118, v58
	v_fmac_f32_e32 v11, v119, v59
	ds_read_b128 v[56:59], v55 offset:2208
	s_waitcnt lgkmcnt(3)
	v_fmac_f32_e32 v10, v116, v60
	v_fmac_f32_e32 v10, v117, v61
	v_fmac_f32_e32 v10, v118, v62
	v_fmac_f32_e32 v10, v119, v63
	ds_read_b128 v[60:63], v55 offset:3232
	s_waitcnt lgkmcnt(3)
	v_fmac_f32_e32 v54, v120, v64
	v_fmac_f32_e32 v54, v121, v65
	v_fmac_f32_e32 v54, v122, v66
	v_fmac_f32_e32 v54, v123, v67
	ds_read_b128 v[64:67], v55 offset:4256
	s_waitcnt lgkmcnt(3)
	v_fmac_f32_e32 v43, v120, v68
	v_fmac_f32_e32 v43, v121, v69
	v_fmac_f32_e32 v43, v122, v70
	v_fmac_f32_e32 v43, v123, v71
	ds_read_b128 v[68:71], v55 offset:5280
	s_waitcnt lgkmcnt(3)
	v_fmac_f32_e32 v42, v120, v56
	v_fmac_f32_e32 v42, v121, v57
	v_fmac_f32_e32 v42, v122, v58
	v_fmac_f32_e32 v42, v123, v59
	ds_read_b128 v[56:59], v55 offset:6304
	s_waitcnt lgkmcnt(3)
	v_fmac_f32_e32 v41, v120, v60
	v_fmac_f32_e32 v41, v121, v61
	v_fmac_f32_e32 v41, v122, v62
	v_fmac_f32_e32 v41, v123, v63
	ds_read_b128 v[60:63], v55 offset:7328
	s_waitcnt lgkmcnt(3)
	v_fmac_f32_e32 v40, v120, v64
	v_fmac_f32_e32 v40, v121, v65
	v_fmac_f32_e32 v40, v122, v66
	v_fmac_f32_e32 v40, v123, v67
	ds_read_b128 v[64:67], v55 offset:8352
	s_waitcnt lgkmcnt(3)
	v_fmac_f32_e32 v39, v120, v68
	v_fmac_f32_e32 v39, v121, v69
	v_fmac_f32_e32 v39, v122, v70
	v_fmac_f32_e32 v39, v123, v71
	ds_read_b128 v[68:71], v55 offset:9376
	s_waitcnt lgkmcnt(3)
	v_fmac_f32_e32 v38, v120, v56
	v_fmac_f32_e32 v38, v121, v57
	v_fmac_f32_e32 v38, v122, v58
	v_fmac_f32_e32 v38, v123, v59
	ds_read_b128 v[56:59], v55 offset:10400
	s_waitcnt lgkmcnt(3)
	v_fmac_f32_e32 v37, v120, v60
	v_fmac_f32_e32 v37, v121, v61
	v_fmac_f32_e32 v37, v122, v62
	v_fmac_f32_e32 v37, v123, v63
	ds_read_b128 v[60:63], v55 offset:11424
	s_waitcnt lgkmcnt(3)
	v_fmac_f32_e32 v36, v120, v64
	v_fmac_f32_e32 v36, v121, v65
	v_fmac_f32_e32 v36, v122, v66
	v_fmac_f32_e32 v36, v123, v67
	ds_read_b128 v[64:67], v55 offset:12448
	s_waitcnt lgkmcnt(3)
	v_fmac_f32_e32 v35, v120, v68
	v_fmac_f32_e32 v35, v121, v69
	v_fmac_f32_e32 v35, v122, v70
	v_fmac_f32_e32 v35, v123, v71
	ds_read_b128 v[68:71], v55 offset:13472
	s_waitcnt lgkmcnt(3)
	v_fmac_f32_e32 v34, v120, v56
	v_fmac_f32_e32 v34, v121, v57
	v_fmac_f32_e32 v34, v122, v58
	v_fmac_f32_e32 v34, v123, v59
	ds_read_b128 v[56:59], v55 offset:14496
	s_waitcnt lgkmcnt(3)
	v_fmac_f32_e32 v33, v120, v60
	v_fmac_f32_e32 v33, v121, v61
	v_fmac_f32_e32 v33, v122, v62
	v_fmac_f32_e32 v33, v123, v63
	ds_read_b128 v[60:63], v55 offset:15520
	s_waitcnt lgkmcnt(3)
	v_fmac_f32_e32 v32, v120, v64
	v_fmac_f32_e32 v32, v121, v65
	v_fmac_f32_e32 v32, v122, v66
	v_fmac_f32_e32 v32, v123, v67
	ds_read_b128 v[64:67], v55 offset:16544
	s_waitcnt lgkmcnt(3)
	v_fmac_f32_e32 v31, v120, v68
	v_fmac_f32_e32 v31, v121, v69
	v_fmac_f32_e32 v31, v122, v70
	v_fmac_f32_e32 v31, v123, v71
	ds_read_b128 v[68:71], v55 offset:17568
	s_waitcnt lgkmcnt(3)
	v_fmac_f32_e32 v30, v120, v56
	v_fmac_f32_e32 v30, v121, v57
	v_fmac_f32_e32 v30, v122, v58
	v_fmac_f32_e32 v30, v123, v59
	ds_read_b128 v[56:59], v55 offset:18592
	s_waitcnt lgkmcnt(3)
	v_fmac_f32_e32 v29, v120, v60
	v_fmac_f32_e32 v29, v121, v61
	v_fmac_f32_e32 v29, v122, v62
	v_fmac_f32_e32 v29, v123, v63
	ds_read_b128 v[60:63], v55 offset:19616
	s_waitcnt lgkmcnt(3)
	v_fmac_f32_e32 v28, v120, v64
	v_fmac_f32_e32 v28, v121, v65
	v_fmac_f32_e32 v28, v122, v66
	v_fmac_f32_e32 v28, v123, v67
	ds_read_b128 v[64:67], v55 offset:20640
	s_waitcnt lgkmcnt(3)
	v_fmac_f32_e32 v27, v120, v68
	v_fmac_f32_e32 v27, v121, v69
	v_fmac_f32_e32 v27, v122, v70
	v_fmac_f32_e32 v27, v123, v71
	ds_read_b128 v[68:71], v55 offset:21664
	s_waitcnt lgkmcnt(3)
	v_fmac_f32_e32 v26, v120, v56
	v_fmac_f32_e32 v26, v121, v57
	v_fmac_f32_e32 v26, v122, v58
	v_fmac_f32_e32 v26, v123, v59
	ds_read_b128 v[56:59], v55 offset:22688
	s_waitcnt lgkmcnt(3)
	v_fmac_f32_e32 v25, v120, v60
	v_fmac_f32_e32 v25, v121, v61
	v_fmac_f32_e32 v25, v122, v62
	v_fmac_f32_e32 v25, v123, v63
	ds_read_b128 v[60:63], v55 offset:23712
	s_waitcnt lgkmcnt(3)
	v_fmac_f32_e32 v24, v120, v64
	v_fmac_f32_e32 v24, v121, v65
	v_fmac_f32_e32 v24, v122, v66
	v_fmac_f32_e32 v24, v123, v67
	ds_read_b128 v[64:67], v55 offset:24736
	s_waitcnt lgkmcnt(3)
	v_fmac_f32_e32 v23, v120, v68
	v_fmac_f32_e32 v23, v121, v69
	v_fmac_f32_e32 v23, v122, v70
	v_fmac_f32_e32 v23, v123, v71
	ds_read_b128 v[68:71], v55 offset:25760
	s_waitcnt lgkmcnt(3)
	v_fmac_f32_e32 v22, v120, v56
	v_fmac_f32_e32 v22, v121, v57
	v_fmac_f32_e32 v22, v122, v58
	v_fmac_f32_e32 v22, v123, v59
	ds_read_b128 v[56:59], v55 offset:26784
	s_waitcnt lgkmcnt(3)
	v_fmac_f32_e32 v21, v120, v60
	v_fmac_f32_e32 v21, v121, v61
	v_fmac_f32_e32 v21, v122, v62
	v_fmac_f32_e32 v21, v123, v63
	ds_read_b128 v[60:63], v55 offset:27808
	s_waitcnt lgkmcnt(3)
	v_fmac_f32_e32 v20, v120, v64
	v_fmac_f32_e32 v20, v121, v65
	v_fmac_f32_e32 v20, v122, v66
	v_fmac_f32_e32 v20, v123, v67
	ds_read_b128 v[64:67], v55 offset:28832
	s_waitcnt lgkmcnt(3)
	v_fmac_f32_e32 v17, v120, v68
	v_fmac_f32_e32 v17, v121, v69
	v_fmac_f32_e32 v17, v122, v70
	v_fmac_f32_e32 v17, v123, v71
	ds_read_b128 v[68:71], v55 offset:29856
	s_waitcnt lgkmcnt(3)
	v_fmac_f32_e32 v16, v120, v56
	v_fmac_f32_e32 v16, v121, v57
	v_fmac_f32_e32 v16, v122, v58
	v_fmac_f32_e32 v16, v123, v59
	ds_read_b128 v[56:59], v55 offset:30880
	s_waitcnt lgkmcnt(3)
	v_fmac_f32_e32 v15, v120, v60
	v_fmac_f32_e32 v15, v121, v61
	v_fmac_f32_e32 v15, v122, v62
	v_fmac_f32_e32 v15, v123, v63
	ds_read_b128 v[60:63], v55 offset:31904
	s_waitcnt lgkmcnt(3)
	v_fmac_f32_e32 v14, v120, v64
	v_fmac_f32_e32 v14, v121, v65
	v_fmac_f32_e32 v14, v122, v66
	v_fmac_f32_e32 v14, v123, v67
	ds_read_b128 v[64:67], v55 offset:32928
	s_waitcnt lgkmcnt(3)
	v_fmac_f32_e32 v13, v120, v68
	v_fmac_f32_e32 v13, v121, v69
	v_fmac_f32_e32 v13, v122, v70
	v_fmac_f32_e32 v13, v123, v71
	ds_read_b128 v[68:71], v55 offset:176
	s_waitcnt lgkmcnt(3)
	v_fmac_f32_e32 v12, v120, v56
	v_fmac_f32_e32 v12, v121, v57
	v_fmac_f32_e32 v12, v122, v58
	v_fmac_f32_e32 v12, v123, v59
	ds_read_b128 v[56:59], v55 offset:1200
	s_waitcnt lgkmcnt(3)
	v_fmac_f32_e32 v11, v120, v60
	v_fmac_f32_e32 v11, v121, v61
	v_fmac_f32_e32 v11, v122, v62
	v_fmac_f32_e32 v11, v123, v63
	ds_read_b128 v[60:63], v55 offset:2224
	s_waitcnt lgkmcnt(3)
	v_fmac_f32_e32 v10, v120, v64
	v_fmac_f32_e32 v10, v121, v65
	v_fmac_f32_e32 v10, v122, v66
	v_fmac_f32_e32 v10, v123, v67
	ds_read_b128 v[64:67], v55 offset:3248
	s_waitcnt lgkmcnt(3)
	v_fmac_f32_e32 v54, v124, v68
	v_fmac_f32_e32 v54, v125, v69
	v_fmac_f32_e32 v54, v126, v70
	v_fmac_f32_e32 v54, v127, v71
	ds_read_b128 v[68:71], v55 offset:4272
	s_waitcnt lgkmcnt(3)
	v_fmac_f32_e32 v43, v124, v56
	v_fmac_f32_e32 v43, v125, v57
	v_fmac_f32_e32 v43, v126, v58
	v_fmac_f32_e32 v43, v127, v59
	ds_read_b128 v[56:59], v55 offset:5296
	s_waitcnt lgkmcnt(3)
	v_fmac_f32_e32 v42, v124, v60
	v_fmac_f32_e32 v42, v125, v61
	v_fmac_f32_e32 v42, v126, v62
	v_fmac_f32_e32 v42, v127, v63
	ds_read_b128 v[60:63], v55 offset:6320
	s_waitcnt lgkmcnt(3)
	v_fmac_f32_e32 v41, v124, v64
	v_fmac_f32_e32 v41, v125, v65
	v_fmac_f32_e32 v41, v126, v66
	v_fmac_f32_e32 v41, v127, v67
	ds_read_b128 v[64:67], v55 offset:7344
	s_waitcnt lgkmcnt(3)
	v_fmac_f32_e32 v40, v124, v68
	v_fmac_f32_e32 v40, v125, v69
	v_fmac_f32_e32 v40, v126, v70
	v_fmac_f32_e32 v40, v127, v71
	ds_read_b128 v[68:71], v55 offset:8368
	s_waitcnt lgkmcnt(3)
	v_fmac_f32_e32 v39, v124, v56
	v_fmac_f32_e32 v39, v125, v57
	v_fmac_f32_e32 v39, v126, v58
	v_fmac_f32_e32 v39, v127, v59
	ds_read_b128 v[56:59], v55 offset:9392
	s_waitcnt lgkmcnt(3)
	v_fmac_f32_e32 v38, v124, v60
	v_fmac_f32_e32 v38, v125, v61
	v_fmac_f32_e32 v38, v126, v62
	v_fmac_f32_e32 v38, v127, v63
	ds_read_b128 v[60:63], v55 offset:10416
	s_waitcnt lgkmcnt(3)
	v_fmac_f32_e32 v37, v124, v64
	v_fmac_f32_e32 v37, v125, v65
	v_fmac_f32_e32 v37, v126, v66
	v_fmac_f32_e32 v37, v127, v67
	ds_read_b128 v[64:67], v55 offset:11440
	s_waitcnt lgkmcnt(3)
	v_fmac_f32_e32 v36, v124, v68
	v_fmac_f32_e32 v36, v125, v69
	v_fmac_f32_e32 v36, v126, v70
	v_fmac_f32_e32 v36, v127, v71
	ds_read_b128 v[68:71], v55 offset:12464
	s_waitcnt lgkmcnt(3)
	v_fmac_f32_e32 v35, v124, v56
	v_fmac_f32_e32 v35, v125, v57
	v_fmac_f32_e32 v35, v126, v58
	v_fmac_f32_e32 v35, v127, v59
	ds_read_b128 v[56:59], v55 offset:13488
	s_waitcnt lgkmcnt(3)
	v_fmac_f32_e32 v34, v124, v60
	v_fmac_f32_e32 v34, v125, v61
	v_fmac_f32_e32 v34, v126, v62
	v_fmac_f32_e32 v34, v127, v63
	ds_read_b128 v[60:63], v55 offset:14512
	s_waitcnt lgkmcnt(3)
	v_fmac_f32_e32 v33, v124, v64
	v_fmac_f32_e32 v33, v125, v65
	v_fmac_f32_e32 v33, v126, v66
	v_fmac_f32_e32 v33, v127, v67
	ds_read_b128 v[64:67], v55 offset:15536
	s_waitcnt lgkmcnt(3)
	v_fmac_f32_e32 v32, v124, v68
	v_fmac_f32_e32 v32, v125, v69
	v_fmac_f32_e32 v32, v126, v70
	v_fmac_f32_e32 v32, v127, v71
	ds_read_b128 v[68:71], v55 offset:16560
	s_waitcnt lgkmcnt(3)
	v_fmac_f32_e32 v31, v124, v56
	v_fmac_f32_e32 v31, v125, v57
	v_fmac_f32_e32 v31, v126, v58
	v_fmac_f32_e32 v31, v127, v59
	ds_read_b128 v[56:59], v55 offset:17584
	s_waitcnt lgkmcnt(3)
	v_fmac_f32_e32 v30, v124, v60
	v_fmac_f32_e32 v30, v125, v61
	v_fmac_f32_e32 v30, v126, v62
	v_fmac_f32_e32 v30, v127, v63
	ds_read_b128 v[60:63], v55 offset:18608
	s_waitcnt lgkmcnt(3)
	v_fmac_f32_e32 v29, v124, v64
	v_fmac_f32_e32 v29, v125, v65
	v_fmac_f32_e32 v29, v126, v66
	v_fmac_f32_e32 v29, v127, v67
	ds_read_b128 v[64:67], v55 offset:19632
	s_waitcnt lgkmcnt(3)
	v_fmac_f32_e32 v28, v124, v68
	v_fmac_f32_e32 v28, v125, v69
	v_fmac_f32_e32 v28, v126, v70
	v_fmac_f32_e32 v28, v127, v71
	ds_read_b128 v[68:71], v55 offset:20656
	s_waitcnt lgkmcnt(3)
	v_fmac_f32_e32 v27, v124, v56
	v_fmac_f32_e32 v27, v125, v57
	v_fmac_f32_e32 v27, v126, v58
	v_fmac_f32_e32 v27, v127, v59
	ds_read_b128 v[56:59], v55 offset:21680
	s_waitcnt lgkmcnt(3)
	v_fmac_f32_e32 v26, v124, v60
	v_fmac_f32_e32 v26, v125, v61
	v_fmac_f32_e32 v26, v126, v62
	v_fmac_f32_e32 v26, v127, v63
	ds_read_b128 v[60:63], v55 offset:22704
	s_waitcnt lgkmcnt(3)
	v_fmac_f32_e32 v25, v124, v64
	v_fmac_f32_e32 v25, v125, v65
	v_fmac_f32_e32 v25, v126, v66
	v_fmac_f32_e32 v25, v127, v67
	ds_read_b128 v[64:67], v55 offset:23728
	s_waitcnt lgkmcnt(3)
	v_fmac_f32_e32 v24, v124, v68
	v_fmac_f32_e32 v24, v125, v69
	v_fmac_f32_e32 v24, v126, v70
	v_fmac_f32_e32 v24, v127, v71
	ds_read_b128 v[68:71], v55 offset:24752
	s_waitcnt lgkmcnt(3)
	v_fmac_f32_e32 v23, v124, v56
	v_fmac_f32_e32 v23, v125, v57
	v_fmac_f32_e32 v23, v126, v58
	v_fmac_f32_e32 v23, v127, v59
	ds_read_b128 v[56:59], v55 offset:25776
	s_waitcnt lgkmcnt(3)
	v_fmac_f32_e32 v22, v124, v60
	v_fmac_f32_e32 v22, v125, v61
	v_fmac_f32_e32 v22, v126, v62
	v_fmac_f32_e32 v22, v127, v63
	ds_read_b128 v[60:63], v55 offset:26800
	s_waitcnt lgkmcnt(3)
	v_fmac_f32_e32 v21, v124, v64
	v_fmac_f32_e32 v21, v125, v65
	v_fmac_f32_e32 v21, v126, v66
	v_fmac_f32_e32 v21, v127, v67
	ds_read_b128 v[64:67], v55 offset:27824
	s_waitcnt lgkmcnt(3)
	v_fmac_f32_e32 v20, v124, v68
	v_fmac_f32_e32 v20, v125, v69
	v_fmac_f32_e32 v20, v126, v70
	v_fmac_f32_e32 v20, v127, v71
	ds_read_b128 v[68:71], v55 offset:28848
	s_waitcnt lgkmcnt(3)
	v_fmac_f32_e32 v17, v124, v56
	v_fmac_f32_e32 v17, v125, v57
	v_fmac_f32_e32 v17, v126, v58
	v_fmac_f32_e32 v17, v127, v59
	ds_read_b128 v[56:59], v55 offset:29872
	s_waitcnt lgkmcnt(3)
	v_fmac_f32_e32 v16, v124, v60
	v_fmac_f32_e32 v16, v125, v61
	v_fmac_f32_e32 v16, v126, v62
	v_fmac_f32_e32 v16, v127, v63
	ds_read_b128 v[60:63], v55 offset:30896
	s_waitcnt lgkmcnt(3)
	v_fmac_f32_e32 v15, v124, v64
	v_fmac_f32_e32 v15, v125, v65
	v_fmac_f32_e32 v15, v126, v66
	v_fmac_f32_e32 v15, v127, v67
	ds_read_b128 v[64:67], v55 offset:31920
	s_waitcnt lgkmcnt(3)
	v_fmac_f32_e32 v14, v124, v68
	v_fmac_f32_e32 v14, v125, v69
	v_fmac_f32_e32 v14, v126, v70
	v_fmac_f32_e32 v14, v127, v71
	ds_read_b128 v[68:71], v55 offset:32944
	s_waitcnt lgkmcnt(3)
	v_fmac_f32_e32 v13, v124, v56
	v_fmac_f32_e32 v13, v125, v57
	v_fmac_f32_e32 v13, v126, v58
	v_fmac_f32_e32 v13, v127, v59
	ds_read_b128 v[56:59], v55 offset:192
	s_waitcnt lgkmcnt(3)
	v_fmac_f32_e32 v12, v124, v60
	v_fmac_f32_e32 v12, v125, v61
	v_fmac_f32_e32 v12, v126, v62
	v_fmac_f32_e32 v12, v127, v63
	ds_read_b128 v[60:63], v55 offset:1216
	s_waitcnt lgkmcnt(3)
	v_fmac_f32_e32 v11, v124, v64
	v_fmac_f32_e32 v11, v125, v65
	v_fmac_f32_e32 v11, v126, v66
	v_fmac_f32_e32 v11, v127, v67
	ds_read_b128 v[64:67], v55 offset:2240
	s_waitcnt lgkmcnt(3)
	v_fmac_f32_e32 v10, v124, v68
	v_fmac_f32_e32 v10, v125, v69
	v_fmac_f32_e32 v10, v126, v70
	v_fmac_f32_e32 v10, v127, v71
	ds_read_b128 v[68:71], v55 offset:3264
	s_waitcnt lgkmcnt(3)
	v_fmac_f32_e32 v54, v128, v56
	v_fmac_f32_e32 v54, v129, v57
	v_fmac_f32_e32 v54, v130, v58
	v_fmac_f32_e32 v54, v131, v59
	ds_read_b128 v[56:59], v55 offset:4288
	s_waitcnt lgkmcnt(3)
	v_fmac_f32_e32 v43, v128, v60
	v_fmac_f32_e32 v43, v129, v61
	v_fmac_f32_e32 v43, v130, v62
	v_fmac_f32_e32 v43, v131, v63
	ds_read_b128 v[60:63], v55 offset:5312
	s_waitcnt lgkmcnt(3)
	v_fmac_f32_e32 v42, v128, v64
	v_fmac_f32_e32 v42, v129, v65
	v_fmac_f32_e32 v42, v130, v66
	v_fmac_f32_e32 v42, v131, v67
	ds_read_b128 v[64:67], v55 offset:6336
	s_waitcnt lgkmcnt(3)
	v_fmac_f32_e32 v41, v128, v68
	v_fmac_f32_e32 v41, v129, v69
	v_fmac_f32_e32 v41, v130, v70
	v_fmac_f32_e32 v41, v131, v71
	ds_read_b128 v[68:71], v55 offset:7360
	s_waitcnt lgkmcnt(3)
	v_fmac_f32_e32 v40, v128, v56
	v_fmac_f32_e32 v40, v129, v57
	v_fmac_f32_e32 v40, v130, v58
	v_fmac_f32_e32 v40, v131, v59
	ds_read_b128 v[56:59], v55 offset:8384
	s_waitcnt lgkmcnt(3)
	v_fmac_f32_e32 v39, v128, v60
	v_fmac_f32_e32 v39, v129, v61
	v_fmac_f32_e32 v39, v130, v62
	v_fmac_f32_e32 v39, v131, v63
	ds_read_b128 v[60:63], v55 offset:9408
	s_waitcnt lgkmcnt(3)
	v_fmac_f32_e32 v38, v128, v64
	v_fmac_f32_e32 v38, v129, v65
	v_fmac_f32_e32 v38, v130, v66
	v_fmac_f32_e32 v38, v131, v67
	ds_read_b128 v[64:67], v55 offset:10432
	s_waitcnt lgkmcnt(3)
	v_fmac_f32_e32 v37, v128, v68
	v_fmac_f32_e32 v37, v129, v69
	v_fmac_f32_e32 v37, v130, v70
	v_fmac_f32_e32 v37, v131, v71
	ds_read_b128 v[68:71], v55 offset:11456
	s_waitcnt lgkmcnt(3)
	v_fmac_f32_e32 v36, v128, v56
	v_fmac_f32_e32 v36, v129, v57
	v_fmac_f32_e32 v36, v130, v58
	v_fmac_f32_e32 v36, v131, v59
	ds_read_b128 v[56:59], v55 offset:12480
	s_waitcnt lgkmcnt(3)
	v_fmac_f32_e32 v35, v128, v60
	v_fmac_f32_e32 v35, v129, v61
	v_fmac_f32_e32 v35, v130, v62
	v_fmac_f32_e32 v35, v131, v63
	ds_read_b128 v[60:63], v55 offset:13504
	s_waitcnt lgkmcnt(3)
	v_fmac_f32_e32 v34, v128, v64
	v_fmac_f32_e32 v34, v129, v65
	v_fmac_f32_e32 v34, v130, v66
	v_fmac_f32_e32 v34, v131, v67
	ds_read_b128 v[64:67], v55 offset:14528
	s_waitcnt lgkmcnt(3)
	v_fmac_f32_e32 v33, v128, v68
	v_fmac_f32_e32 v33, v129, v69
	v_fmac_f32_e32 v33, v130, v70
	v_fmac_f32_e32 v33, v131, v71
	ds_read_b128 v[68:71], v55 offset:15552
	s_waitcnt lgkmcnt(3)
	v_fmac_f32_e32 v32, v128, v56
	v_fmac_f32_e32 v32, v129, v57
	v_fmac_f32_e32 v32, v130, v58
	v_fmac_f32_e32 v32, v131, v59
	ds_read_b128 v[56:59], v55 offset:16576
	s_waitcnt lgkmcnt(3)
	v_fmac_f32_e32 v31, v128, v60
	v_fmac_f32_e32 v31, v129, v61
	v_fmac_f32_e32 v31, v130, v62
	v_fmac_f32_e32 v31, v131, v63
	ds_read_b128 v[60:63], v55 offset:17600
	s_waitcnt lgkmcnt(3)
	v_fmac_f32_e32 v30, v128, v64
	v_fmac_f32_e32 v30, v129, v65
	v_fmac_f32_e32 v30, v130, v66
	v_fmac_f32_e32 v30, v131, v67
	ds_read_b128 v[64:67], v55 offset:18624
	s_waitcnt lgkmcnt(3)
	v_fmac_f32_e32 v29, v128, v68
	v_fmac_f32_e32 v29, v129, v69
	v_fmac_f32_e32 v29, v130, v70
	v_fmac_f32_e32 v29, v131, v71
	ds_read_b128 v[68:71], v55 offset:19648
	s_waitcnt lgkmcnt(3)
	v_fmac_f32_e32 v28, v128, v56
	v_fmac_f32_e32 v28, v129, v57
	v_fmac_f32_e32 v28, v130, v58
	v_fmac_f32_e32 v28, v131, v59
	ds_read_b128 v[56:59], v55 offset:20672
	s_waitcnt lgkmcnt(3)
	v_fmac_f32_e32 v27, v128, v60
	v_fmac_f32_e32 v27, v129, v61
	v_fmac_f32_e32 v27, v130, v62
	v_fmac_f32_e32 v27, v131, v63
	ds_read_b128 v[60:63], v55 offset:21696
	s_waitcnt lgkmcnt(3)
	v_fmac_f32_e32 v26, v128, v64
	v_fmac_f32_e32 v26, v129, v65
	v_fmac_f32_e32 v26, v130, v66
	v_fmac_f32_e32 v26, v131, v67
	ds_read_b128 v[64:67], v55 offset:22720
	s_waitcnt lgkmcnt(3)
	v_fmac_f32_e32 v25, v128, v68
	v_fmac_f32_e32 v25, v129, v69
	v_fmac_f32_e32 v25, v130, v70
	v_fmac_f32_e32 v25, v131, v71
	ds_read_b128 v[68:71], v55 offset:23744
	s_waitcnt lgkmcnt(3)
	v_fmac_f32_e32 v24, v128, v56
	v_fmac_f32_e32 v24, v129, v57
	v_fmac_f32_e32 v24, v130, v58
	v_fmac_f32_e32 v24, v131, v59
	ds_read_b128 v[56:59], v55 offset:24768
	s_waitcnt lgkmcnt(3)
	v_fmac_f32_e32 v23, v128, v60
	v_fmac_f32_e32 v23, v129, v61
	v_fmac_f32_e32 v23, v130, v62
	v_fmac_f32_e32 v23, v131, v63
	ds_read_b128 v[60:63], v55 offset:25792
	s_waitcnt lgkmcnt(3)
	v_fmac_f32_e32 v22, v128, v64
	v_fmac_f32_e32 v22, v129, v65
	v_fmac_f32_e32 v22, v130, v66
	v_fmac_f32_e32 v22, v131, v67
	ds_read_b128 v[64:67], v55 offset:26816
	s_waitcnt lgkmcnt(3)
	v_fmac_f32_e32 v21, v128, v68
	v_fmac_f32_e32 v21, v129, v69
	v_fmac_f32_e32 v21, v130, v70
	v_fmac_f32_e32 v21, v131, v71
	ds_read_b128 v[68:71], v55 offset:27840
	s_waitcnt lgkmcnt(3)
	v_fmac_f32_e32 v20, v128, v56
	v_fmac_f32_e32 v20, v129, v57
	v_fmac_f32_e32 v20, v130, v58
	v_fmac_f32_e32 v20, v131, v59
	ds_read_b128 v[56:59], v55 offset:28864
	s_waitcnt lgkmcnt(3)
	v_fmac_f32_e32 v17, v128, v60
	v_fmac_f32_e32 v17, v129, v61
	v_fmac_f32_e32 v17, v130, v62
	v_fmac_f32_e32 v17, v131, v63
	ds_read_b128 v[60:63], v55 offset:29888
	s_waitcnt lgkmcnt(3)
	v_fmac_f32_e32 v16, v128, v64
	v_fmac_f32_e32 v16, v129, v65
	v_fmac_f32_e32 v16, v130, v66
	v_fmac_f32_e32 v16, v131, v67
	ds_read_b128 v[64:67], v55 offset:30912
	s_waitcnt lgkmcnt(3)
	v_fmac_f32_e32 v15, v128, v68
	v_fmac_f32_e32 v15, v129, v69
	v_fmac_f32_e32 v15, v130, v70
	v_fmac_f32_e32 v15, v131, v71
	ds_read_b128 v[68:71], v55 offset:31936
	s_waitcnt lgkmcnt(3)
	v_fmac_f32_e32 v14, v128, v56
	v_fmac_f32_e32 v14, v129, v57
	v_fmac_f32_e32 v14, v130, v58
	v_fmac_f32_e32 v14, v131, v59
	ds_read_b128 v[56:59], v55 offset:32960
	s_waitcnt lgkmcnt(3)
	v_fmac_f32_e32 v13, v128, v60
	v_fmac_f32_e32 v13, v129, v61
	v_fmac_f32_e32 v13, v130, v62
	v_fmac_f32_e32 v13, v131, v63
	ds_read_b128 v[60:63], v55 offset:208
	s_waitcnt lgkmcnt(3)
	v_fmac_f32_e32 v12, v128, v64
	v_fmac_f32_e32 v12, v129, v65
	v_fmac_f32_e32 v12, v130, v66
	v_fmac_f32_e32 v12, v131, v67
	ds_read_b128 v[64:67], v55 offset:1232
	s_waitcnt lgkmcnt(3)
	v_fmac_f32_e32 v11, v128, v68
	v_fmac_f32_e32 v11, v129, v69
	v_fmac_f32_e32 v11, v130, v70
	v_fmac_f32_e32 v11, v131, v71
	ds_read_b128 v[68:71], v55 offset:2256
	s_waitcnt lgkmcnt(3)
	v_fmac_f32_e32 v10, v128, v56
	v_fmac_f32_e32 v10, v129, v57
	v_fmac_f32_e32 v10, v130, v58
	v_fmac_f32_e32 v10, v131, v59
	ds_read_b128 v[56:59], v55 offset:3280
	s_waitcnt lgkmcnt(3)
	v_fmac_f32_e32 v54, v132, v60
	v_fmac_f32_e32 v54, v133, v61
	v_fmac_f32_e32 v54, v134, v62
	v_fmac_f32_e32 v54, v135, v63
	ds_read_b128 v[60:63], v55 offset:4304
	s_waitcnt lgkmcnt(3)
	v_fmac_f32_e32 v43, v132, v64
	v_fmac_f32_e32 v43, v133, v65
	v_fmac_f32_e32 v43, v134, v66
	v_fmac_f32_e32 v43, v135, v67
	ds_read_b128 v[64:67], v55 offset:5328
	s_waitcnt lgkmcnt(3)
	v_fmac_f32_e32 v42, v132, v68
	v_fmac_f32_e32 v42, v133, v69
	v_fmac_f32_e32 v42, v134, v70
	v_fmac_f32_e32 v42, v135, v71
	ds_read_b128 v[68:71], v55 offset:6352
	s_waitcnt lgkmcnt(3)
	v_fmac_f32_e32 v41, v132, v56
	v_fmac_f32_e32 v41, v133, v57
	v_fmac_f32_e32 v41, v134, v58
	v_fmac_f32_e32 v41, v135, v59
	ds_read_b128 v[56:59], v55 offset:7376
	s_waitcnt lgkmcnt(3)
	v_fmac_f32_e32 v40, v132, v60
	v_fmac_f32_e32 v40, v133, v61
	v_fmac_f32_e32 v40, v134, v62
	v_fmac_f32_e32 v40, v135, v63
	ds_read_b128 v[60:63], v55 offset:8400
	s_waitcnt lgkmcnt(3)
	v_fmac_f32_e32 v39, v132, v64
	v_fmac_f32_e32 v39, v133, v65
	v_fmac_f32_e32 v39, v134, v66
	v_fmac_f32_e32 v39, v135, v67
	ds_read_b128 v[64:67], v55 offset:9424
	s_waitcnt lgkmcnt(3)
	v_fmac_f32_e32 v38, v132, v68
	v_fmac_f32_e32 v38, v133, v69
	v_fmac_f32_e32 v38, v134, v70
	v_fmac_f32_e32 v38, v135, v71
	ds_read_b128 v[68:71], v55 offset:10448
	s_waitcnt lgkmcnt(3)
	v_fmac_f32_e32 v37, v132, v56
	v_fmac_f32_e32 v37, v133, v57
	v_fmac_f32_e32 v37, v134, v58
	v_fmac_f32_e32 v37, v135, v59
	ds_read_b128 v[56:59], v55 offset:11472
	s_waitcnt lgkmcnt(3)
	v_fmac_f32_e32 v36, v132, v60
	v_fmac_f32_e32 v36, v133, v61
	v_fmac_f32_e32 v36, v134, v62
	v_fmac_f32_e32 v36, v135, v63
	ds_read_b128 v[60:63], v55 offset:12496
	s_waitcnt lgkmcnt(3)
	v_fmac_f32_e32 v35, v132, v64
	v_fmac_f32_e32 v35, v133, v65
	v_fmac_f32_e32 v35, v134, v66
	v_fmac_f32_e32 v35, v135, v67
	ds_read_b128 v[64:67], v55 offset:13520
	s_waitcnt lgkmcnt(3)
	v_fmac_f32_e32 v34, v132, v68
	v_fmac_f32_e32 v34, v133, v69
	v_fmac_f32_e32 v34, v134, v70
	v_fmac_f32_e32 v34, v135, v71
	ds_read_b128 v[68:71], v55 offset:14544
	s_waitcnt lgkmcnt(3)
	v_fmac_f32_e32 v33, v132, v56
	v_fmac_f32_e32 v33, v133, v57
	v_fmac_f32_e32 v33, v134, v58
	v_fmac_f32_e32 v33, v135, v59
	ds_read_b128 v[56:59], v55 offset:15568
	s_waitcnt lgkmcnt(3)
	v_fmac_f32_e32 v32, v132, v60
	v_fmac_f32_e32 v32, v133, v61
	v_fmac_f32_e32 v32, v134, v62
	v_fmac_f32_e32 v32, v135, v63
	ds_read_b128 v[60:63], v55 offset:16592
	s_waitcnt lgkmcnt(3)
	v_fmac_f32_e32 v31, v132, v64
	v_fmac_f32_e32 v31, v133, v65
	v_fmac_f32_e32 v31, v134, v66
	v_fmac_f32_e32 v31, v135, v67
	ds_read_b128 v[64:67], v55 offset:17616
	s_waitcnt lgkmcnt(3)
	v_fmac_f32_e32 v30, v132, v68
	v_fmac_f32_e32 v30, v133, v69
	v_fmac_f32_e32 v30, v134, v70
	v_fmac_f32_e32 v30, v135, v71
	ds_read_b128 v[68:71], v55 offset:18640
	s_waitcnt lgkmcnt(3)
	v_fmac_f32_e32 v29, v132, v56
	v_fmac_f32_e32 v29, v133, v57
	v_fmac_f32_e32 v29, v134, v58
	v_fmac_f32_e32 v29, v135, v59
	ds_read_b128 v[56:59], v55 offset:19664
	s_waitcnt lgkmcnt(3)
	v_fmac_f32_e32 v28, v132, v60
	v_fmac_f32_e32 v28, v133, v61
	v_fmac_f32_e32 v28, v134, v62
	v_fmac_f32_e32 v28, v135, v63
	ds_read_b128 v[60:63], v55 offset:20688
	s_waitcnt lgkmcnt(3)
	v_fmac_f32_e32 v27, v132, v64
	v_fmac_f32_e32 v27, v133, v65
	v_fmac_f32_e32 v27, v134, v66
	v_fmac_f32_e32 v27, v135, v67
	ds_read_b128 v[64:67], v55 offset:21712
	s_waitcnt lgkmcnt(3)
	v_fmac_f32_e32 v26, v132, v68
	v_fmac_f32_e32 v26, v133, v69
	v_fmac_f32_e32 v26, v134, v70
	v_fmac_f32_e32 v26, v135, v71
	ds_read_b128 v[68:71], v55 offset:22736
	s_waitcnt lgkmcnt(3)
	v_fmac_f32_e32 v25, v132, v56
	v_fmac_f32_e32 v25, v133, v57
	v_fmac_f32_e32 v25, v134, v58
	v_fmac_f32_e32 v25, v135, v59
	ds_read_b128 v[56:59], v55 offset:23760
	s_waitcnt lgkmcnt(3)
	v_fmac_f32_e32 v24, v132, v60
	v_fmac_f32_e32 v24, v133, v61
	v_fmac_f32_e32 v24, v134, v62
	v_fmac_f32_e32 v24, v135, v63
	ds_read_b128 v[60:63], v55 offset:24784
	s_waitcnt lgkmcnt(3)
	v_fmac_f32_e32 v23, v132, v64
	v_fmac_f32_e32 v23, v133, v65
	v_fmac_f32_e32 v23, v134, v66
	v_fmac_f32_e32 v23, v135, v67
	ds_read_b128 v[64:67], v55 offset:25808
	s_waitcnt lgkmcnt(3)
	v_fmac_f32_e32 v22, v132, v68
	v_fmac_f32_e32 v22, v133, v69
	v_fmac_f32_e32 v22, v134, v70
	v_fmac_f32_e32 v22, v135, v71
	ds_read_b128 v[68:71], v55 offset:26832
	s_waitcnt lgkmcnt(3)
	v_fmac_f32_e32 v21, v132, v56
	v_fmac_f32_e32 v21, v133, v57
	v_fmac_f32_e32 v21, v134, v58
	v_fmac_f32_e32 v21, v135, v59
	ds_read_b128 v[56:59], v55 offset:27856
	s_waitcnt lgkmcnt(3)
	v_fmac_f32_e32 v20, v132, v60
	v_fmac_f32_e32 v20, v133, v61
	v_fmac_f32_e32 v20, v134, v62
	v_fmac_f32_e32 v20, v135, v63
	ds_read_b128 v[60:63], v55 offset:28880
	s_waitcnt lgkmcnt(3)
	v_fmac_f32_e32 v17, v132, v64
	v_fmac_f32_e32 v17, v133, v65
	v_fmac_f32_e32 v17, v134, v66
	v_fmac_f32_e32 v17, v135, v67
	ds_read_b128 v[64:67], v55 offset:29904
	s_waitcnt lgkmcnt(3)
	v_fmac_f32_e32 v16, v132, v68
	v_fmac_f32_e32 v16, v133, v69
	v_fmac_f32_e32 v16, v134, v70
	v_fmac_f32_e32 v16, v135, v71
	ds_read_b128 v[68:71], v55 offset:30928
	s_waitcnt lgkmcnt(3)
	v_fmac_f32_e32 v15, v132, v56
	v_fmac_f32_e32 v15, v133, v57
	v_fmac_f32_e32 v15, v134, v58
	v_fmac_f32_e32 v15, v135, v59
	ds_read_b128 v[56:59], v55 offset:31952
	s_waitcnt lgkmcnt(3)
	v_fmac_f32_e32 v14, v132, v60
	v_fmac_f32_e32 v14, v133, v61
	v_fmac_f32_e32 v14, v134, v62
	v_fmac_f32_e32 v14, v135, v63
	ds_read_b128 v[60:63], v55 offset:32976
	s_waitcnt lgkmcnt(3)
	v_fmac_f32_e32 v13, v132, v64
	v_fmac_f32_e32 v13, v133, v65
	v_fmac_f32_e32 v13, v134, v66
	v_fmac_f32_e32 v13, v135, v67
	ds_read_b128 v[64:67], v55 offset:224
	s_waitcnt lgkmcnt(3)
	v_fmac_f32_e32 v12, v132, v68
	v_fmac_f32_e32 v12, v133, v69
	v_fmac_f32_e32 v12, v134, v70
	v_fmac_f32_e32 v12, v135, v71
	ds_read_b128 v[68:71], v55 offset:1248
	s_waitcnt lgkmcnt(3)
	v_fmac_f32_e32 v11, v132, v56
	v_fmac_f32_e32 v11, v133, v57
	v_fmac_f32_e32 v11, v134, v58
	v_fmac_f32_e32 v11, v135, v59
	ds_read_b128 v[56:59], v55 offset:2272
	s_waitcnt lgkmcnt(3)
	v_fmac_f32_e32 v10, v132, v60
	v_fmac_f32_e32 v10, v133, v61
	v_fmac_f32_e32 v10, v134, v62
	v_fmac_f32_e32 v10, v135, v63
	ds_read_b128 v[60:63], v55 offset:3296
	s_waitcnt lgkmcnt(3)
	v_fmac_f32_e32 v54, v136, v64
	v_fmac_f32_e32 v54, v137, v65
	v_fmac_f32_e32 v54, v138, v66
	v_fmac_f32_e32 v54, v139, v67
	ds_read_b128 v[64:67], v55 offset:4320
	s_waitcnt lgkmcnt(3)
	v_fmac_f32_e32 v43, v136, v68
	v_fmac_f32_e32 v43, v137, v69
	v_fmac_f32_e32 v43, v138, v70
	v_fmac_f32_e32 v43, v139, v71
	ds_read_b128 v[68:71], v55 offset:5344
	s_waitcnt lgkmcnt(3)
	v_fmac_f32_e32 v42, v136, v56
	v_fmac_f32_e32 v42, v137, v57
	v_fmac_f32_e32 v42, v138, v58
	v_fmac_f32_e32 v42, v139, v59
	ds_read_b128 v[56:59], v55 offset:6368
	s_waitcnt lgkmcnt(3)
	v_fmac_f32_e32 v41, v136, v60
	v_fmac_f32_e32 v41, v137, v61
	v_fmac_f32_e32 v41, v138, v62
	v_fmac_f32_e32 v41, v139, v63
	ds_read_b128 v[60:63], v55 offset:7392
	s_waitcnt lgkmcnt(3)
	v_fmac_f32_e32 v40, v136, v64
	v_fmac_f32_e32 v40, v137, v65
	v_fmac_f32_e32 v40, v138, v66
	v_fmac_f32_e32 v40, v139, v67
	ds_read_b128 v[64:67], v55 offset:8416
	s_waitcnt lgkmcnt(3)
	v_fmac_f32_e32 v39, v136, v68
	v_fmac_f32_e32 v39, v137, v69
	v_fmac_f32_e32 v39, v138, v70
	v_fmac_f32_e32 v39, v139, v71
	ds_read_b128 v[68:71], v55 offset:9440
	s_waitcnt lgkmcnt(3)
	v_fmac_f32_e32 v38, v136, v56
	v_fmac_f32_e32 v38, v137, v57
	v_fmac_f32_e32 v38, v138, v58
	v_fmac_f32_e32 v38, v139, v59
	ds_read_b128 v[56:59], v55 offset:10464
	s_waitcnt lgkmcnt(3)
	v_fmac_f32_e32 v37, v136, v60
	v_fmac_f32_e32 v37, v137, v61
	v_fmac_f32_e32 v37, v138, v62
	v_fmac_f32_e32 v37, v139, v63
	ds_read_b128 v[60:63], v55 offset:11488
	s_waitcnt lgkmcnt(3)
	v_fmac_f32_e32 v36, v136, v64
	v_fmac_f32_e32 v36, v137, v65
	v_fmac_f32_e32 v36, v138, v66
	v_fmac_f32_e32 v36, v139, v67
	ds_read_b128 v[64:67], v55 offset:12512
	s_waitcnt lgkmcnt(3)
	v_fmac_f32_e32 v35, v136, v68
	v_fmac_f32_e32 v35, v137, v69
	v_fmac_f32_e32 v35, v138, v70
	v_fmac_f32_e32 v35, v139, v71
	ds_read_b128 v[68:71], v55 offset:13536
	s_waitcnt lgkmcnt(3)
	v_fmac_f32_e32 v34, v136, v56
	v_fmac_f32_e32 v34, v137, v57
	v_fmac_f32_e32 v34, v138, v58
	v_fmac_f32_e32 v34, v139, v59
	ds_read_b128 v[56:59], v55 offset:14560
	s_waitcnt lgkmcnt(3)
	v_fmac_f32_e32 v33, v136, v60
	v_fmac_f32_e32 v33, v137, v61
	v_fmac_f32_e32 v33, v138, v62
	v_fmac_f32_e32 v33, v139, v63
	ds_read_b128 v[60:63], v55 offset:15584
	s_waitcnt lgkmcnt(3)
	v_fmac_f32_e32 v32, v136, v64
	v_fmac_f32_e32 v32, v137, v65
	v_fmac_f32_e32 v32, v138, v66
	v_fmac_f32_e32 v32, v139, v67
	ds_read_b128 v[64:67], v55 offset:16608
	s_waitcnt lgkmcnt(3)
	v_fmac_f32_e32 v31, v136, v68
	v_fmac_f32_e32 v31, v137, v69
	v_fmac_f32_e32 v31, v138, v70
	v_fmac_f32_e32 v31, v139, v71
	ds_read_b128 v[68:71], v55 offset:17632
	s_waitcnt lgkmcnt(3)
	v_fmac_f32_e32 v30, v136, v56
	v_fmac_f32_e32 v30, v137, v57
	v_fmac_f32_e32 v30, v138, v58
	v_fmac_f32_e32 v30, v139, v59
	ds_read_b128 v[56:59], v55 offset:18656
	s_waitcnt lgkmcnt(3)
	v_fmac_f32_e32 v29, v136, v60
	v_fmac_f32_e32 v29, v137, v61
	v_fmac_f32_e32 v29, v138, v62
	v_fmac_f32_e32 v29, v139, v63
	ds_read_b128 v[60:63], v55 offset:19680
	s_waitcnt lgkmcnt(3)
	v_fmac_f32_e32 v28, v136, v64
	v_fmac_f32_e32 v28, v137, v65
	v_fmac_f32_e32 v28, v138, v66
	v_fmac_f32_e32 v28, v139, v67
	ds_read_b128 v[64:67], v55 offset:20704
	s_waitcnt lgkmcnt(3)
	v_fmac_f32_e32 v27, v136, v68
	v_fmac_f32_e32 v27, v137, v69
	v_fmac_f32_e32 v27, v138, v70
	v_fmac_f32_e32 v27, v139, v71
	ds_read_b128 v[68:71], v55 offset:21728
	s_waitcnt lgkmcnt(3)
	v_fmac_f32_e32 v26, v136, v56
	v_fmac_f32_e32 v26, v137, v57
	v_fmac_f32_e32 v26, v138, v58
	v_fmac_f32_e32 v26, v139, v59
	ds_read_b128 v[56:59], v55 offset:22752
	s_waitcnt lgkmcnt(3)
	v_fmac_f32_e32 v25, v136, v60
	v_fmac_f32_e32 v25, v137, v61
	v_fmac_f32_e32 v25, v138, v62
	v_fmac_f32_e32 v25, v139, v63
	ds_read_b128 v[60:63], v55 offset:23776
	s_waitcnt lgkmcnt(3)
	v_fmac_f32_e32 v24, v136, v64
	v_fmac_f32_e32 v24, v137, v65
	v_fmac_f32_e32 v24, v138, v66
	v_fmac_f32_e32 v24, v139, v67
	ds_read_b128 v[64:67], v55 offset:24800
	s_waitcnt lgkmcnt(3)
	v_fmac_f32_e32 v23, v136, v68
	v_fmac_f32_e32 v23, v137, v69
	v_fmac_f32_e32 v23, v138, v70
	v_fmac_f32_e32 v23, v139, v71
	ds_read_b128 v[68:71], v55 offset:25824
	s_waitcnt lgkmcnt(3)
	v_fmac_f32_e32 v22, v136, v56
	v_fmac_f32_e32 v22, v137, v57
	v_fmac_f32_e32 v22, v138, v58
	v_fmac_f32_e32 v22, v139, v59
	ds_read_b128 v[56:59], v55 offset:26848
	s_waitcnt lgkmcnt(3)
	v_fmac_f32_e32 v21, v136, v60
	v_fmac_f32_e32 v21, v137, v61
	v_fmac_f32_e32 v21, v138, v62
	v_fmac_f32_e32 v21, v139, v63
	ds_read_b128 v[60:63], v55 offset:27872
	s_waitcnt lgkmcnt(3)
	v_fmac_f32_e32 v20, v136, v64
	v_fmac_f32_e32 v20, v137, v65
	v_fmac_f32_e32 v20, v138, v66
	v_fmac_f32_e32 v20, v139, v67
	ds_read_b128 v[64:67], v55 offset:28896
	s_waitcnt lgkmcnt(3)
	v_fmac_f32_e32 v17, v136, v68
	v_fmac_f32_e32 v17, v137, v69
	v_fmac_f32_e32 v17, v138, v70
	v_fmac_f32_e32 v17, v139, v71
	ds_read_b128 v[68:71], v55 offset:29920
	s_waitcnt lgkmcnt(3)
	v_fmac_f32_e32 v16, v136, v56
	v_fmac_f32_e32 v16, v137, v57
	v_fmac_f32_e32 v16, v138, v58
	v_fmac_f32_e32 v16, v139, v59
	ds_read_b128 v[56:59], v55 offset:30944
	s_waitcnt lgkmcnt(3)
	v_fmac_f32_e32 v15, v136, v60
	v_fmac_f32_e32 v15, v137, v61
	v_fmac_f32_e32 v15, v138, v62
	v_fmac_f32_e32 v15, v139, v63
	ds_read_b128 v[60:63], v55 offset:31968
	s_waitcnt lgkmcnt(3)
	v_fmac_f32_e32 v14, v136, v64
	v_fmac_f32_e32 v14, v137, v65
	v_fmac_f32_e32 v14, v138, v66
	v_fmac_f32_e32 v14, v139, v67
	ds_read_b128 v[64:67], v55 offset:32992
	s_waitcnt lgkmcnt(3)
	v_fmac_f32_e32 v13, v136, v68
	v_fmac_f32_e32 v13, v137, v69
	v_fmac_f32_e32 v13, v138, v70
	v_fmac_f32_e32 v13, v139, v71
	ds_read_b128 v[68:71], v55 offset:240
	s_waitcnt lgkmcnt(3)
	v_fmac_f32_e32 v12, v136, v56
	v_fmac_f32_e32 v12, v137, v57
	v_fmac_f32_e32 v12, v138, v58
	v_fmac_f32_e32 v12, v139, v59
	ds_read_b128 v[56:59], v55 offset:1264
	s_waitcnt lgkmcnt(3)
	v_fmac_f32_e32 v11, v136, v60
	v_fmac_f32_e32 v11, v137, v61
	v_fmac_f32_e32 v11, v138, v62
	v_fmac_f32_e32 v11, v139, v63
	ds_read_b128 v[60:63], v55 offset:2288
	s_waitcnt lgkmcnt(3)
	v_fmac_f32_e32 v10, v136, v64
	v_fmac_f32_e32 v10, v137, v65
	v_fmac_f32_e32 v10, v138, v66
	v_fmac_f32_e32 v10, v139, v67
	ds_read_b128 v[64:67], v55 offset:3312
	s_waitcnt lgkmcnt(3)
	v_fmac_f32_e32 v54, v140, v68
	v_fmac_f32_e32 v54, v141, v69
	v_fmac_f32_e32 v54, v142, v70
	v_fmac_f32_e32 v54, v143, v71
	ds_read_b128 v[68:71], v55 offset:4336
	s_waitcnt lgkmcnt(3)
	v_fmac_f32_e32 v43, v140, v56
	v_fmac_f32_e32 v43, v141, v57
	v_fmac_f32_e32 v43, v142, v58
	v_fmac_f32_e32 v43, v143, v59
	ds_read_b128 v[56:59], v55 offset:5360
	s_waitcnt lgkmcnt(3)
	v_fmac_f32_e32 v42, v140, v60
	v_fmac_f32_e32 v42, v141, v61
	v_fmac_f32_e32 v42, v142, v62
	v_fmac_f32_e32 v42, v143, v63
	ds_read_b128 v[60:63], v55 offset:6384
	s_waitcnt lgkmcnt(3)
	v_fmac_f32_e32 v41, v140, v64
	v_fmac_f32_e32 v41, v141, v65
	v_fmac_f32_e32 v41, v142, v66
	v_fmac_f32_e32 v41, v143, v67
	ds_read_b128 v[64:67], v55 offset:7408
	s_waitcnt lgkmcnt(3)
	v_fmac_f32_e32 v40, v140, v68
	v_fmac_f32_e32 v40, v141, v69
	v_fmac_f32_e32 v40, v142, v70
	v_fmac_f32_e32 v40, v143, v71
	ds_read_b128 v[68:71], v55 offset:8432
	s_waitcnt lgkmcnt(3)
	v_fmac_f32_e32 v39, v140, v56
	v_fmac_f32_e32 v39, v141, v57
	v_fmac_f32_e32 v39, v142, v58
	v_fmac_f32_e32 v39, v143, v59
	ds_read_b128 v[56:59], v55 offset:9456
	s_waitcnt lgkmcnt(3)
	v_fmac_f32_e32 v38, v140, v60
	v_fmac_f32_e32 v38, v141, v61
	v_fmac_f32_e32 v38, v142, v62
	v_fmac_f32_e32 v38, v143, v63
	ds_read_b128 v[60:63], v55 offset:10480
	s_waitcnt lgkmcnt(3)
	v_fmac_f32_e32 v37, v140, v64
	v_fmac_f32_e32 v37, v141, v65
	v_fmac_f32_e32 v37, v142, v66
	v_fmac_f32_e32 v37, v143, v67
	ds_read_b128 v[64:67], v55 offset:11504
	s_waitcnt lgkmcnt(3)
	v_fmac_f32_e32 v36, v140, v68
	v_fmac_f32_e32 v36, v141, v69
	v_fmac_f32_e32 v36, v142, v70
	v_fmac_f32_e32 v36, v143, v71
	ds_read_b128 v[68:71], v55 offset:12528
	s_waitcnt lgkmcnt(3)
	v_fmac_f32_e32 v35, v140, v56
	v_fmac_f32_e32 v35, v141, v57
	v_fmac_f32_e32 v35, v142, v58
	v_fmac_f32_e32 v35, v143, v59
	ds_read_b128 v[56:59], v55 offset:13552
	s_waitcnt lgkmcnt(3)
	v_fmac_f32_e32 v34, v140, v60
	v_fmac_f32_e32 v34, v141, v61
	v_fmac_f32_e32 v34, v142, v62
	v_fmac_f32_e32 v34, v143, v63
	ds_read_b128 v[60:63], v55 offset:14576
	s_waitcnt lgkmcnt(3)
	v_fmac_f32_e32 v33, v140, v64
	v_fmac_f32_e32 v33, v141, v65
	v_fmac_f32_e32 v33, v142, v66
	v_fmac_f32_e32 v33, v143, v67
	ds_read_b128 v[64:67], v55 offset:15600
	s_waitcnt lgkmcnt(3)
	v_fmac_f32_e32 v32, v140, v68
	v_fmac_f32_e32 v32, v141, v69
	v_fmac_f32_e32 v32, v142, v70
	v_fmac_f32_e32 v32, v143, v71
	ds_read_b128 v[68:71], v55 offset:16624
	s_waitcnt lgkmcnt(3)
	v_fmac_f32_e32 v31, v140, v56
	v_fmac_f32_e32 v31, v141, v57
	v_fmac_f32_e32 v31, v142, v58
	v_fmac_f32_e32 v31, v143, v59
	ds_read_b128 v[56:59], v55 offset:17648
	s_waitcnt lgkmcnt(3)
	v_fmac_f32_e32 v30, v140, v60
	v_fmac_f32_e32 v30, v141, v61
	v_fmac_f32_e32 v30, v142, v62
	v_fmac_f32_e32 v30, v143, v63
	ds_read_b128 v[60:63], v55 offset:18672
	s_waitcnt lgkmcnt(3)
	v_fmac_f32_e32 v29, v140, v64
	v_fmac_f32_e32 v29, v141, v65
	v_fmac_f32_e32 v29, v142, v66
	v_fmac_f32_e32 v29, v143, v67
	ds_read_b128 v[64:67], v55 offset:19696
	s_waitcnt lgkmcnt(3)
	v_fmac_f32_e32 v28, v140, v68
	v_fmac_f32_e32 v28, v141, v69
	v_fmac_f32_e32 v28, v142, v70
	v_fmac_f32_e32 v28, v143, v71
	ds_read_b128 v[68:71], v55 offset:20720
	s_waitcnt lgkmcnt(3)
	v_fmac_f32_e32 v27, v140, v56
	v_fmac_f32_e32 v27, v141, v57
	v_fmac_f32_e32 v27, v142, v58
	v_fmac_f32_e32 v27, v143, v59
	ds_read_b128 v[56:59], v55 offset:21744
	s_waitcnt lgkmcnt(3)
	v_fmac_f32_e32 v26, v140, v60
	v_fmac_f32_e32 v26, v141, v61
	v_fmac_f32_e32 v26, v142, v62
	v_fmac_f32_e32 v26, v143, v63
	ds_read_b128 v[60:63], v55 offset:22768
	s_waitcnt lgkmcnt(3)
	v_fmac_f32_e32 v25, v140, v64
	v_fmac_f32_e32 v25, v141, v65
	v_fmac_f32_e32 v25, v142, v66
	v_fmac_f32_e32 v25, v143, v67
	ds_read_b128 v[64:67], v55 offset:23792
	s_waitcnt lgkmcnt(3)
	v_fmac_f32_e32 v24, v140, v68
	v_fmac_f32_e32 v24, v141, v69
	v_fmac_f32_e32 v24, v142, v70
	v_fmac_f32_e32 v24, v143, v71
	ds_read_b128 v[68:71], v55 offset:24816
	s_waitcnt lgkmcnt(3)
	v_fmac_f32_e32 v23, v140, v56
	v_fmac_f32_e32 v23, v141, v57
	v_fmac_f32_e32 v23, v142, v58
	v_fmac_f32_e32 v23, v143, v59
	ds_read_b128 v[56:59], v55 offset:25840
	s_waitcnt lgkmcnt(3)
	v_fmac_f32_e32 v22, v140, v60
	v_fmac_f32_e32 v22, v141, v61
	v_fmac_f32_e32 v22, v142, v62
	v_fmac_f32_e32 v22, v143, v63
	ds_read_b128 v[60:63], v55 offset:26864
	s_waitcnt lgkmcnt(3)
	v_fmac_f32_e32 v21, v140, v64
	v_fmac_f32_e32 v21, v141, v65
	v_fmac_f32_e32 v21, v142, v66
	v_fmac_f32_e32 v21, v143, v67
	ds_read_b128 v[64:67], v55 offset:27888
	s_waitcnt lgkmcnt(3)
	v_fmac_f32_e32 v20, v140, v68
	v_fmac_f32_e32 v20, v141, v69
	v_fmac_f32_e32 v20, v142, v70
	v_fmac_f32_e32 v20, v143, v71
	ds_read_b128 v[68:71], v55 offset:28912
	s_waitcnt lgkmcnt(3)
	v_fmac_f32_e32 v17, v140, v56
	v_fmac_f32_e32 v17, v141, v57
	v_fmac_f32_e32 v17, v142, v58
	v_fmac_f32_e32 v17, v143, v59
	ds_read_b128 v[56:59], v55 offset:29936
	s_waitcnt lgkmcnt(3)
	v_fmac_f32_e32 v16, v140, v60
	v_fmac_f32_e32 v16, v141, v61
	v_fmac_f32_e32 v16, v142, v62
	v_fmac_f32_e32 v16, v143, v63
	ds_read_b128 v[60:63], v55 offset:30960
	s_waitcnt lgkmcnt(3)
	v_fmac_f32_e32 v15, v140, v64
	v_fmac_f32_e32 v15, v141, v65
	v_fmac_f32_e32 v15, v142, v66
	v_fmac_f32_e32 v15, v143, v67
	ds_read_b128 v[64:67], v55 offset:31984
	s_waitcnt lgkmcnt(3)
	v_fmac_f32_e32 v14, v140, v68
	v_fmac_f32_e32 v14, v141, v69
	v_fmac_f32_e32 v14, v142, v70
	v_fmac_f32_e32 v14, v143, v71
	ds_read_b128 v[68:71], v55 offset:33008
	s_waitcnt lgkmcnt(3)
	v_fmac_f32_e32 v13, v140, v56
	v_fmac_f32_e32 v13, v141, v57
	v_fmac_f32_e32 v13, v142, v58
	v_fmac_f32_e32 v13, v143, v59
	s_waitcnt lgkmcnt(2)
	v_fmac_f32_e32 v12, v140, v60
	v_fmac_f32_e32 v12, v141, v61
	v_fmac_f32_e32 v12, v142, v62
	v_fmac_f32_e32 v12, v143, v63
	s_waitcnt lgkmcnt(1)
	v_fmac_f32_e32 v11, v140, v64
	v_fmac_f32_e32 v11, v141, v65
	v_fmac_f32_e32 v11, v142, v66
	v_fmac_f32_e32 v11, v143, v67
	s_waitcnt lgkmcnt(0)
	v_fmac_f32_e32 v10, v140, v68
	v_fmac_f32_e32 v10, v141, v69
	v_fmac_f32_e32 v10, v142, v70
	v_fmac_f32_e32 v10, v143, v71
	ds_write2st64_b32 v4, v54, v43 offset0:132 offset1:134
	ds_write2st64_b32 v4, v42, v41 offset0:136 offset1:138
	ds_write2st64_b32 v4, v40, v39 offset0:140 offset1:142
	ds_write2st64_b32 v4, v38, v37 offset0:144 offset1:146
	ds_write2st64_b32 v4, v36, v35 offset0:148 offset1:150
	ds_write2st64_b32 v4, v34, v33 offset0:152 offset1:154
	ds_write2st64_b32 v4, v32, v31 offset0:156 offset1:158
	ds_write2st64_b32 v4, v30, v29 offset0:160 offset1:162
	ds_write2st64_b32 v4, v28, v27 offset0:164 offset1:166
	ds_write2st64_b32 v4, v26, v25 offset0:168 offset1:170
	ds_write2st64_b32 v4, v24, v23 offset0:172 offset1:174
	ds_write2st64_b32 v4, v22, v21 offset0:176 offset1:178
	ds_write2st64_b32 v4, v20, v17 offset0:180 offset1:182
	ds_write2st64_b32 v4, v16, v15 offset0:184 offset1:186
	ds_write2st64_b32 v4, v14, v13 offset0:188 offset1:190
	ds_write2st64_b32 v4, v12, v11 offset0:192 offset1:194
	ds_write_b32 v4, v10 offset:50176
	s_waitcnt lgkmcnt(0)
	s_barrier
	s_and_saveexec_b64 s[14:15], s[4:5]
	s_cbranch_execz .LBB0_550
	s_lshl_b32 s3, s18, 1
	s_add_i32 s2, s3, s2
	s_mul_i32 s2, s2, 33
	s_ashr_i32 s3, s2, 31
	v_lshl_add_u64 v[10:11], s[12:13], 2, v[6:7]
	s_mov_b64 s[10:11], -1
	v_mov_b32_e32 v12, v176
	s_and_saveexec_b64 s[12:13], s[6:7]
	s_cbranch_execz .LBB0_565
	s_mov_b32 s18, s2
	s_mov_b32 s19, s3
	s_mov_b64 s[20:21], 0
	v_mov_b32_e32 v14, v49
	v_mov_b32_e32 v15, v53
	v_mov_b64_e32 v[12:13], v[176:177]

.LBB0_861:
	s_waitcnt lgkmcnt(0)
	global_load_dword v7, v193, s[80:81] sc1
	global_load_dword v0, v193, s[80:81] offset:256 sc1
	global_load_dword v1, v193, s[80:81] offset:512 sc1
	global_load_dword v2, v193, s[80:81] offset:768 sc1
	global_load_dword v3, v193, s[80:81] offset:1024 sc1
	global_load_dword v4, v193, s[80:81] offset:1280 sc1
	global_load_dword v5, v193, s[80:81] offset:1536 sc1
	global_load_dword v6, v193, s[80:81] offset:1792 sc1
	global_load_dword v8, v193, s[80:81] offset:2048 sc1
	global_load_dword v9, v193, s[80:81] offset:2304 sc1
	global_load_dword v10, v193, s[80:81] offset:2560 sc1
	global_load_dword v11, v193, s[80:81] offset:2816 sc1
	global_load_dword v12, v193, s[80:81] offset:3072 sc1
	global_load_dword v13, v193, s[80:81] offset:3328 sc1
	global_load_dword v14, v193, s[80:81] offset:3584 sc1
	global_load_dword v15, v193, s[80:81] offset:3840 sc1
	s_mov_b64 s[4:5], -1
	s_mov_b64 s[2:3], -1
	s_waitcnt vmcnt(0)
	v_add_u32_e32 v16, v0, v7
	v_add_u32_e32 v16, v16, v1
	v_add_u32_e32 v16, v16, v2
	v_add_u32_e32 v16, v16, v3
	v_add_u32_e32 v16, v16, v4
	v_add_u32_e32 v16, v16, v5
	v_add_u32_e32 v16, v16, v6
	v_add_u32_e32 v16, v16, v8
	v_add_u32_e32 v16, v16, v9
	v_add_u32_e32 v16, v16, v10
	v_add_u32_e32 v16, v16, v11
	v_add_u32_e32 v16, v16, v12
	v_add_u32_e32 v16, v16, v13
	v_add_u32_e32 v16, v16, v14
	v_add_u32_e32 v16, v16, v15
	v_cmp_eq_u32_e32 vcc, s73, v16
	s_cbranch_vccnz .LBB0_860
	s_and_b32 s2, s8, 0xff
	s_cmp_eq_u32 s2, 0
	s_mov_b64 s[2:3], -1
	s_mov_b64 s[6:7], -1
	s_sleep 1
	s_cbranch_scc1 .LBB0_865
	s_and_b64 vcc, exec, s[6:7]
	s_cbranch_vccz .LBB0_860
